# attention main loop rewritten by hand: alternating score accumulator sets, P kept in place, K/V fragment prefetch 3 pairs deep, Q frags 8-11 held in registers, softmax VALU spread between MFMAs
# speedup vs baseline: 1.0241x; 1.0241x over previous
; __device__ __forceinline__ int v_st(int k, int c) { const int kk = (k & ~0xC) | ((k & 4) << 1) | ((k & 8) >> 1); return ((kk >> 3) * 4 + (c >> 5)) * 512 + ((kk & 7) * 32 + (c & 31)) * 2; }
; __device__ __forceinline__ void attn_unit(const bf16* __restrict__ Qb, const bf16* __restrict__ KN, const bf16* __restrict__ KR, ...
;     ...
;     const float rsn = 1.0f / sqrtf(ssn * (1.0f / 128) + 1e-6f), rsr = 1.0f / sqrtf(ssr * (1.0f / 64) + 1e-6f);
; #pragma unroll
;     for (int d0 = 0; d0 < 8; ++d0) { u32x4 w;
; #pragma unroll
;       for (int e2 = 0; e2 < 4; ++e2) { const int d = d0 * 16 + hi * 8 + 2 * e2;
;         const float v0 = __builtin_bit_cast(float, ((unsigned)(unsigned short)raw[d0][2 * e2]) << 16) * rsn * qn_g[d], v1 = __builtin_bit_cast(float, ((unsigned)(unsigned short)raw[d0][2 * e2 + 1]) << 16) * rsn * qn_g[d + 1];
;         w[e2] = cvtpk(v0, v1); }
;       qr[d0] = *reinterpret_cast<bf16x8*>(&w); }
;     const int npos = npos0 < 0 ? -1 : npos0 + wid * QBLK + r32;
; #pragma unroll
;     for (int a = 0; a < 2; ++a) { u32x4 w0, w1; const int pos = a ? (npos & 63) : (npos >> 6);
; #pragma unroll
;       for (int e2 = 0; e2 < 4; ++e2) { float o0[2], o1[2];
; #pragma unroll
;         for (int t = 0; t < 2; ++t) { const int e = 2 * e2 + t, f = hi * 8 + e;
;           const float x0 = __builtin_bit_cast(float, ((unsigned)(unsigned short)raw[8 + 2 * a][e]) << 16) * rsr * qr_g[a * 32 + f];
;           const float x1 = __builtin_bit_cast(float, ((unsigned)(unsigned short)raw[9 + 2 * a][e]) << 16) * rsr * qr_g[a * 32 + 16 + f];
;           float c = 1.f, sn = 0.f; if (npos >= 0) { c = rope[(pos * 16 + f) * 2]; sn = rope[(pos * 16 + f) * 2 + 1]; }
;           o0[t] = x0 * c - x1 * sn; o1[t] = x1 * c + x0 * sn; }
;         w0[e2] = cvtpk(o0[0], o0[1]); w1[e2] = cvtpk(o1[0], o1[1]); }
;       qs[(2 * a) * 64] = *reinterpret_cast<bf16x8*>(&w0); qs[(2 * a + 1) * 64] = *reinterpret_cast<bf16x8*>(&w1); }
;   }
;   int kb[4];
; #pragma unroll
;   for (int j = 0; j < 4; ++j) kb[j] = r32 * 384 + ((j * 32 + hi * 16) ^ (((r32 >> 1) & 7) << 4));
;   const int sr = tid >> 4, sc = (tid & 15) * 8, vst0 = v_st(sr, sc), vst1 = v_st(32 + sr, sc);
;   const int knd0 = KSWZ(sr, sc * 2), knd1 = knd0 + 32 * 384, krd = KSWZ(tid >> 3, (16 + (tid & 7)) * 16);
;   const int vb0 = (int)(uintptr_t)V_lds + v_rd_base(lane);
;   bf16x8 vs0, vs1, ks0, ks1, ks2;
.LBB0_106:
	s_or_b64 exec, exec, s[8:9]
	v_mul_f32_e32 v137, v148, v186
	v_mov_b32_e32 v149, v148
	v_mul_f32_e32 v136, v148, v185
	s_waitcnt vmcnt(2)
	v_mul_f32_e32 v137, v137, v173
	v_mul_f32_e32 v136, v136, v174
	v_mul_f32_e32 v173, v137, v143
	v_mul_f32_e32 v174, v137, v142
	v_pk_mul_f32 v[38:39], v[148:149], v[38:39]
	v_fma_f32 v173, v136, v142, -v173
	v_fmac_f32_e32 v174, v136, v143
	s_waitcnt vmcnt(0)
	v_pk_mul_f32 v[142:143], v[38:39], v[164:165]
	v_mul_f32_e32 v39, v148, v184
	v_mul_f32_e32 v38, v148, v183
	v_mul_f32_e32 v39, v39, v171
	v_mul_f32_e32 v38, v38, v172
	v_mul_f32_e32 v136, v39, v159
	v_fma_f32 v164, v38, v158, -v136
	v_mul_f32_e32 v158, v39, v158
	v_pk_mul_f32 v[36:37], v[148:149], v[36:37]
	v_fmac_f32_e32 v158, v38, v159
	v_pk_mul_f32 v[38:39], v[36:37], v[162:163]
	v_mul_f32_e32 v37, v148, v182
	v_mul_f32_e32 v36, v148, v181
	v_mul_f32_e32 v37, v37, v169
	v_mul_f32_e32 v36, v36, v170
	v_mul_f32_e32 v136, v37, v153
	v_fma_f32 v159, v36, v152, -v136
	v_mul_f32_e32 v152, v37, v152
	v_mul_f32_e32 v37, v148, v180
	v_fmac_f32_e32 v152, v36, v153
	v_mul_f32_e32 v36, v148, v179
	v_mul_f32_e32 v37, v37, v167
	v_pk_mul_f32 v[32:33], v[148:149], v[32:33]
	v_mul_f32_e32 v36, v36, v168
	v_mul_f32_e32 v136, v37, v141
	v_mul_f32_e32 v137, v37, v140
	v_pk_mul_f32 v[32:33], v[32:33], v[144:145]
	v_fma_f32 v136, v36, v140, -v136
	v_fmac_f32_e32 v137, v36, v141
	v_mul_f32_e32 v36, v33, v146
	v_pk_mul_f32 v[34:35], v[148:149], v[34:35]
	v_pk_fma_f32 v[36:37], v[32:33], v[146:147], v[36:37] op_sel:[1,0,0] op_sel_hi:[0,1,0] neg_lo:[1,0,0] neg_hi:[1,0,0]
	v_pk_mul_f32 v[34:35], v[34:35], v[156:157]
	v_mul_f32_e32 v36, v32, v146
	v_pk_fma_f32 v[32:33], v[32:33], v[146:147], v[36:37] op_sel_hi:[1,1,0]
	v_cvt_pk_bf16_f32 v36, v136, v37
	v_mul_f32_e32 v136, v35, v150
	v_cvt_pk_bf16_f32 v32, v137, v33
	v_pk_fma_f32 v[136:137], v[34:35], v[150:151], v[136:137] op_sel:[1,0,0] op_sel_hi:[0,1,0] neg_lo:[1,0,0] neg_hi:[1,0,0]
	v_mul_f32_e32 v136, v34, v150
	v_pk_fma_f32 v[34:35], v[34:35], v[150:151], v[136:137] op_sel_hi:[1,1,0]
	v_cvt_pk_bf16_f32 v37, v159, v137
	v_mul_f32_e32 v34, v39, v154
	v_cvt_pk_bf16_f32 v33, v152, v35
	v_pk_fma_f32 v[34:35], v[38:39], v[154:155], v[34:35] op_sel:[1,0,0] op_sel_hi:[0,1,0] neg_lo:[1,0,0] neg_hi:[1,0,0]
	v_mul_f32_e32 v34, v38, v154
	v_pk_fma_f32 v[38:39], v[38:39], v[154:155], v[34:35] op_sel_hi:[1,1,0]
	s_waitcnt lgkmcnt(2)
	v_add_f32_e32 v34, v188, v189
	v_fmamk_f32 v34, v34, 0x3c000000, v243
	v_mul_f32_e32 v38, 0x4f800000, v34
	v_cmp_gt_f32_e32 vcc, s71, v34
	s_lshl_b32 s2, s39, 9
	v_ashrrev_i32_e32 v162, 4, v178
	v_cndmask_b32_e32 v136, v34, v38, vcc
	v_sqrt_f32_e32 v137, v136
	v_cvt_pk_bf16_f32 v38, v164, v35
	v_cvt_pk_bf16_f32 v34, v158, v39
	v_ashrrev_i32_e32 v163, 31, v162
	v_add_u32_e32 v35, -1, v137
	v_fma_f32 v39, -v35, v137, v136
	v_cmp_ge_f32_e64 s[6:7], 0, v39
	v_add_u32_e32 v39, 1, v137
	v_lshlrev_b32_e32 v158, 3, v178
	v_cndmask_b32_e64 v35, v137, v35, s[6:7]
	v_fma_f32 v137, -v39, v137, v136
	v_cmp_lt_f32_e64 s[6:7], 0, v137
	v_mov_b32_e32 v137, v209
	v_ashrrev_i32_e32 v159, 31, v158
	v_cndmask_b32_e64 v35, v35, v39, s[6:7]
	v_mul_f32_e32 v39, 0x37800000, v35
	v_cndmask_b32_e32 v35, v35, v39, vcc
	v_cmp_class_f32_e32 vcc, v136, v244
	s_mov_b32 s8, 0
	s_mov_b32 s9, s8
	v_cndmask_b32_e32 v35, v35, v136, vcc
	v_div_scale_f32 v39, s[0:1], v35, v35, 1.0
	v_readlane_b32 s0, v254, 20
	v_rcp_f32_e32 v164, v39
	v_readlane_b32 s1, v254, 21
	s_add_u32 s46, s0, s2
	s_addc_u32 s47, s1, 0
	s_add_i32 s0, 0, 0x1e000
	s_cmp_lg_u32 0, -1
	s_cselect_b32 s1, 0, 0
	s_ashr_i32 s11, s10, 31
	v_fma_f32 v136, -v39, v164, 1.0
	v_lshl_add_u64 v[140:141], v[162:163], 0, s[10:11]
	v_fmac_f32_e32 v164, v136, v164
	v_and_b32_e32 v136, 0x78, v158
	v_lshlrev_b64 v[140:141], 11, v[140:141]
	v_lshlrev_b32_e32 v136, 1, v136
	v_lshl_add_u64 v[140:141], s[46:47], 0, v[140:141]
	v_lshl_add_u64 v[140:141], v[140:141], 0, v[136:137]
	s_lshl_b64 s[2:3], s[10:11], 7
	v_add_co_u32_e64 v144, s[6:7], s73, v140
	s_add_u32 s2, s26, s2
	s_nop 0
	v_addc_co_u32_e64 v145, s[6:7], 0, v141, s[6:7]
	global_load_dwordx4 v[146:149], v[140:141], off
	global_load_dwordx4 v[150:153], v[140:141], off offset:256
	global_load_dwordx4 v[154:157], v[144:145], off
	global_load_dwordx4 v[168:171], v[144:145], off offset:256
	s_addc_u32 s3, s27, s3
	v_lshlrev_b64 v[140:141], 1, v[158:159]
	v_lshl_add_u64 v[144:145], s[2:3], 0, v[140:141]
	global_load_dwordx4 v[182:185], v[144:145], off
	v_div_scale_f32 v165, vcc, 1.0, v35, 1.0
	v_mul_f32_e32 v144, v165, v164
	v_fma_f32 v145, -v39, v144, v165
	v_fmac_f32_e32 v144, v145, v164
	v_fma_f32 v39, -v39, v144, v165
	v_div_fmas_f32 v39, v39, v164, v144
	v_div_fixup_f32 v144, v39, v35, 1.0
	v_pk_mul_f32 v[96:97], v[144:145], v[96:97] op_sel_hi:[0,1]
	v_pk_mul_f32 v[28:29], v[28:29], v[96:97]
	s_movk_i32 s2, 0x180
	v_cvt_pk_bf16_f32 v96, v28, v29
	v_pk_mul_f32 v[28:29], v[144:145], v[134:135] op_sel_hi:[0,1]
	v_pk_mul_f32 v[28:29], v[30:31], v[28:29]
	s_sub_i32 s45, s12, s42
	v_cvt_pk_bf16_f32 v97, v28, v29
	v_pk_mul_f32 v[28:29], v[144:145], v[98:99] op_sel_hi:[0,1]
	v_pk_mul_f32 v[24:25], v[24:25], v[28:29]
	s_mov_b32 s10, s8
	v_cvt_pk_bf16_f32 v98, v24, v25
	v_pk_mul_f32 v[24:25], v[144:145], v[104:105] op_sel_hi:[0,1]
	v_pk_mul_f32 v[24:25], v[26:27], v[24:25]
	s_mov_b32 s11, s8
	v_cvt_pk_bf16_f32 v99, v24, v25
	v_pk_mul_f32 v[24:25], v[144:145], v[100:101] op_sel_hi:[0,1]
	v_pk_mul_f32 v[20:21], v[20:21], v[24:25]
	s_mov_b32 s12, s8
	v_cvt_pk_bf16_f32 v100, v20, v21
	v_pk_mul_f32 v[20:21], v[144:145], v[102:103] op_sel_hi:[0,1]
	v_pk_mul_f32 v[20:21], v[22:23], v[20:21]
	s_mov_b32 s13, s8
	v_cvt_pk_bf16_f32 v101, v20, v21
; __device__ __forceinline__ int v_st(int k, int c) { const int kk = (k & ~0xC) | ((k & 4) << 1) | ((k & 8) >> 1); return ((kk >> 3) * 4 + (c >> 5)) * 512 + ((kk & 7) * 32 + (c & 31)) * 2; }
; __device__ __forceinline__ int v_rd_base(int lane) { return ((lane & 3) << 3) | (((lane >> 2) & 3) << 6) | (((lane >> 4) & 1) << 5) | (((lane >> 5) & 1) << 8); }
; #define SLOAD(k0) do { const long rb = KROW(k0); const bf16* pn = KN + (rb + sr) * LDKN + sc; \
;     ks0 = *reinterpret_cast<const bf16x8*>(pn); ks1 = *reinterpret_cast<const bf16x8*>(pn + 32 * LDKN); vs0 = *reinterpret_cast<const bf16x8*>(pn + 128); vs1 = *reinterpret_cast<const bf16x8*>(pn + 32 * LDKN + 128); \
;     ks2 = *reinterpret_cast<const bf16x8*>(KR + rb * LDKR + tid * 8); } while (0)
; #define SWAIT() asm volatile("s_waitcnt vmcnt(0)" ::: "memory")
; __device__ __forceinline__ void qkt(f32x16& p0, f32x16& p1, const char* Ks, const bf16x8* qr, const bf16x8* qs, const int* kb) {
;   p0 = f32x16{}; p1 = f32x16{};
; #pragma unroll
;   for (int d0 = 0; d0 < 12; ++d0) { const int off = kb[d0 & 3] + (d0 >> 2) * 128;
;     bf16x8 b0 = *reinterpret_cast<const bf16x8*>(Ks + off);
;     bf16x8 b1 = *reinterpret_cast<const bf16x8*>(Ks + off + 32 * 384);
;     const bf16x8 q = d0 < 8 ? qr[d0 < 8 ? d0 : 0] : qs[(d0 - 8) * 64];
;     p0 = __builtin_amdgcn_mfma_f32_32x32x16_bf16(b0, q, p0, 0, 0, 0);
;     p1 = __builtin_amdgcn_mfma_f32_32x32x16_bf16(b1, q, p1, 0, 0, 0); }
; __device__ __forceinline__ void attn_unit(const bf16* __restrict__ Qb, const bf16* __restrict__ KN, const bf16* __restrict__ KR, ...
;     ...
;       qs[(2 * a) * 64] = *reinterpret_cast<bf16x8*>(&w0); qs[(2 * a + 1) * 64] = *reinterpret_cast<bf16x8*>(&w1); }
;   }
;   int kb[4];
; #pragma unroll
;   for (int j = 0; j < 4; ++j) kb[j] = r32 * 384 + ((j * 32 + hi * 16) ^ (((r32 >> 1) & 7) << 4));
;   const int sr = tid >> 4, sc = (tid & 15) * 8, vst0 = v_st(sr, sc), vst1 = v_st(32 + sr, sc);
;   const int knd0 = KSWZ(sr, sc * 2), knd1 = knd0 + 32 * 384, krd = KSWZ(tid >> 3, (16 + (tid & 7)) * 16);
;   const int vb0 = (int)(uintptr_t)V_lds + v_rd_base(lane);
;   bf16x8 vs0, vs1, ks0, ks1, ks2;
;     ...
;   f32x16 pA0, pA1, pB0, pB1; float mnA, mnB, alA, alB; bf16x8 pa0, pa1, pa2, pa3; const int NT = seq / KVBLK;
;   SLOAD(0); SWAIT(); SWRITE(0); __syncthreads();
;   qkt(pA0, pA1, K_lds, qr, qs, kb); partialSM(pA0, pA1, m_reg, mnA, alA);
	v_pk_mul_f32 v[20:21], v[144:145], v[46:47] op_sel_hi:[0,1]
	v_pk_mul_f32 v[16:17], v[16:17], v[20:21]
	v_mul_f32_e32 v20, v143, v138
	v_pk_fma_f32 v[20:21], v[142:143], v[138:139], v[20:21] op_sel:[1,0,0] op_sel_hi:[0,1,0] neg_lo:[1,0,0] neg_hi:[1,0,0]
	v_mul_f32_e32 v20, v142, v138
	v_pk_fma_f32 v[22:23], v[142:143], v[138:139], v[20:21] op_sel_hi:[1,1,0]
	v_cvt_pk_bf16_f32 v39, v173, v21
	v_and_b32_e32 v20, 0xfffff0, v162
	v_lshlrev_b32_e32 v21, 1, v162
	v_and_or_b32 v20, v21, 8, v20
	v_cvt_pk_bf16_f32 v35, v174, v23
	v_lshrrev_b32_e32 v21, 1, v162
	v_lshrrev_b32_e32 v20, 1, v20
	v_bfe_u32 v22, v158, 5, 2
	v_and_b32_e32 v23, 3, v162
	v_or_b32_e32 v20, v20, v22
	v_and_or_b32 v21, v21, 4, v23
	v_lshlrev_b32_e32 v20, 9, v20
	v_lshlrev_b32_e32 v21, 6, v21
	v_and_b32_e32 v23, 48, v136
	v_or3_b32 v174, v20, v21, v23
	v_add_u32_e32 v20, 32, v162
	v_and_b32_e32 v24, 0xfffff0, v20
	v_lshlrev_b32_e32 v20, 1, v20
	v_and_or_b32 v20, v20, 8, v24
	v_lshrrev_b32_e32 v20, 1, v20
	v_or_b32_e32 v20, v20, v22
	v_lshlrev_b32_e32 v20, 9, v20
	v_or3_b32 v175, v20, v21, v23
	v_lshrrev_b32_e32 v21, 1, v178
	v_mul_lo_u32 v20, v162, s2
	v_and_b32_e32 v21, 0x70, v21
	v_xad_u32 v179, v136, v21, v20
	v_lshlrev_b32_e32 v21, 4, v178
	v_lshrrev_b32_e32 v20, 3, v178
	v_and_b32_e32 v21, 0x70, v21
	v_mul_u32_u24_e32 v142, 0x180, v176
	v_and_b32_e32 v143, 0x70, v158
	v_mul_lo_u32 v20, v20, s2
	v_or_b32_e32 v21, 0x100, v21
	v_and_b32_e32 v22, 0x70, v178
	ds_write_b128 v161, v[36:39] offset:2048
	ds_write_b128 v161, v[32:35] offset:3072
	v_bitop3_b32 v173, v208, v142, v143 bitop3:0xde
	v_xad_u32 v180, v21, v22, v20
	v_add_u32_e32 v145, 0, v174
	v_add_u32_e32 v158, 0, v175
	v_add_u32_e32 v20, 0, v179
	s_waitcnt vmcnt(0)
	s_waitcnt vmcnt(3)
	ds_write_b128 v145, v[150:153]
	s_waitcnt vmcnt(1)
	ds_write_b128 v158, v[168:171]
	ds_write_b128 v20, v[146:149] offset:49152
	ds_write_b128 v20, v[154:157] offset:61440
	v_add_u32_e32 v20, 0, v180
	v_add_u32_e32 v159, 0, v173
	s_waitcnt vmcnt(0)
	ds_write_b128 v20, v[182:185] offset:49152
	s_waitcnt lgkmcnt(0)
	s_barrier
	ds_read_b128 v[20:23], v159 offset:49152
	v_cvt_pk_bf16_f32 v102, v16, v17
	v_pk_mul_f32 v[16:17], v[144:145], v[44:45] op_sel_hi:[0,1]
	v_pk_mul_f32 v[16:17], v[18:19], v[16:17]
	ds_read_b128 v[32:35], v159 offset:61440
	ds_read_b128 v[146:149], v159 offset:49280
	v_cvt_pk_bf16_f32 v103, v16, v17
	v_pk_mul_f32 v[16:17], v[144:145], v[42:43] op_sel_hi:[0,1]
	v_pk_mul_f32 v[36:37], v[76:77], v[16:17]
	s_waitcnt lgkmcnt(2)
	v_mfma_f32_32x32x16_bf16 v[16:31], v[20:23], v[96:99], 0
	v_cvt_pk_bf16_f32 v104, v36, v37
	v_or_b32_e32 v36, 32, v208
	v_bitop3_b32 v181, v36, v142, v143 bitop3:0xde
	v_mul_f32_e64 v76, v144, v40
	v_mul_f32_e64 v77, v144, v41
	v_add_u32_e32 v164, 0, v181
	ds_read_b128 v[150:153], v164 offset:49152
	ds_read_b128 v[154:157], v159 offset:49408
	v_pk_mul_f32 v[76:77], v[78:79], v[76:77]
	s_waitcnt lgkmcnt(3)
	v_mfma_f32_32x32x16_bf16 v[32:47], v[32:35], v[96:99], 0
	v_cvt_pk_bf16_f32 v105, v76, v77
	v_mul_f32_e64 v76, v144, v106
	v_mul_f32_e64 v77, v144, v107
	v_mul_f32_e64 v72, v72, v76
	v_mul_f32_e64 v73, v73, v77
	ds_read_b128 v[76:79], v164 offset:61440
	ds_read_b128 v[168:171], v164 offset:49280
	v_cvt_pk_bf16_f32 v106, v72, v73
	v_pk_mul_f32 v[72:73], v[144:145], v[132:133] op_sel_hi:[0,1]
	v_pk_mul_f32 v[138:139], v[74:75], v[72:73]
	s_waitcnt lgkmcnt(3)
	v_mfma_f32_32x32x16_bf16 v[16:31], v[150:153], v[100:103], v[16:31]
	v_or_b32_e32 v72, 64, v208
	v_bitop3_b32 v182, v72, v142, v143 bitop3:0xde
	v_add_u32_e32 v165, 0, v182
	ds_read_b128 v[72:75], v165 offset:49152
	ds_read_b128 v[132:135], v164 offset:49408
	v_cvt_pk_bf16_f32 v107, v138, v139
	s_and_b64 s[2:3], s[4:5], exec
	s_cselect_b32 s2, s44, s45
	s_waitcnt lgkmcnt(3)
	v_mfma_f32_32x32x16_bf16 v[32:47], v[76:79], v[100:103], v[32:47]
	v_mul_f32_e64 v76, v144, v116
	v_mul_f32_e64 v77, v144, v117
	v_mul_f32_e64 v68, v68, v76
	v_mul_f32_e64 v69, v69, v77
	ds_read_b128 v[76:79], v165 offset:61440
	ds_read_b128 v[150:153], v165 offset:49280
	v_cvt_pk_bf16_f32 v116, v68, v69
	v_pk_mul_f32 v[68:69], v[144:145], v[130:131] op_sel_hi:[0,1]
	v_pk_mul_f32 v[68:69], v[70:71], v[68:69]
	s_add_i32 s2, s2, 64
	s_waitcnt lgkmcnt(3)
	v_mfma_f32_32x32x16_bf16 v[16:31], v[72:75], v[104:107], v[16:31]
	v_cvt_pk_bf16_f32 v117, v68, v69
	v_or_b32_e32 v68, 0x60, v208
	v_bitop3_b32 v183, v68, v142, v143 bitop3:0xde
	v_add_u32_e32 v130, 0, v183
	ds_read_b128 v[68:71], v130 offset:49152
	ds_read_b128 v[72:75], v165 offset:49408
	s_ashr_i32 s3, s2, 31
	s_mov_b32 s14, s8
	s_waitcnt lgkmcnt(3)
	v_mfma_f32_32x32x16_bf16 v[32:47], v[76:79], v[104:107], v[32:47]
	v_mul_f32_e64 v76, v144, v118
	v_mul_f32_e64 v77, v144, v119
	v_mul_f32_e64 v64, v64, v76
	v_mul_f32_e64 v65, v65, v77
	v_mul_f32_e64 v76, v144, v108
	v_mul_f32_e64 v77, v144, v109
	v_cvt_pk_bf16_f32 v118, v64, v65
	v_pk_mul_f32 v[64:65], v[144:145], v[128:129] op_sel_hi:[0,1]
	v_pk_mul_f32 v[64:65], v[66:67], v[64:65]
	v_pk_mul_f32 v[60:61], v[60:61], v[76:77]
	v_cvt_pk_bf16_f32 v119, v64, v65
	v_cvt_pk_bf16_f32 v108, v60, v61
	v_pk_mul_f32 v[60:61], v[144:145], v[126:127] op_sel_hi:[0,1]
	s_waitcnt lgkmcnt(1)
	v_mfma_f32_32x32x16_bf16 v[16:31], v[68:71], v[116:119], v[16:31]
	ds_read_b128 v[68:71], v130 offset:61440
	v_mul_f32_e64 v76, v62, v60
	v_mul_f32_e64 v77, v63, v61
	ds_read_b128 v[64:67], v130 offset:49280
	ds_read_b128 v[60:63], v130 offset:49408
	v_cvt_pk_bf16_f32 v109, v76, v77
	s_mov_b32 s15, s8
	s_mov_b32 s16, s8
	s_waitcnt lgkmcnt(2)
; __device__ __forceinline__ int v_st(int k, int c) { const int kk = (k & ~0xC) | ((k & 4) << 1) | ((k & 8) >> 1); return ((kk >> 3) * 4 + (c >> 5)) * 512 + ((kk & 7) * 32 + (c & 31)) * 2; }
; __device__ __forceinline__ int v_rd_base(int lane) { return ((lane & 3) << 3) | (((lane >> 2) & 3) << 6) | (((lane >> 4) & 1) << 5) | (((lane >> 5) & 1) << 8); }
; #define SLOAD(k0) do { const long rb = KROW(k0); const bf16* pn = KN + (rb + sr) * LDKN + sc; \
;     ks0 = *reinterpret_cast<const bf16x8*>(pn); ks1 = *reinterpret_cast<const bf16x8*>(pn + 32 * LDKN); vs0 = *reinterpret_cast<const bf16x8*>(pn + 128); vs1 = *reinterpret_cast<const bf16x8*>(pn + 32 * LDKN + 128); \
;     ks2 = *reinterpret_cast<const bf16x8*>(KR + rb * LDKR + tid * 8); } while (0)
; #define SWRITE(b) do { *(bf16x8*)(V_lds + (b) * SHM_V + vst0) = vs0; *(bf16x8*)(V_lds + (b) * SHM_V + vst1) = vs1; \
;     *(bf16x8*)(K_lds + (b) * SHM_K + knd0) = ks0; *(bf16x8*)(K_lds + (b) * SHM_K + knd1) = ks1; *(bf16x8*)(K_lds + (b) * SHM_K + krd) = ks2; } while (0)
; __device__ __forceinline__ void qkt(f32x16& p0, f32x16& p1, const char* Ks, const bf16x8* qr, const bf16x8* qs, const int* kb) {
;   p0 = f32x16{}; p1 = f32x16{};
; #pragma unroll
;   for (int d0 = 0; d0 < 12; ++d0) { const int off = kb[d0 & 3] + (d0 >> 2) * 128;
;     bf16x8 b0 = *reinterpret_cast<const bf16x8*>(Ks + off);
;     bf16x8 b1 = *reinterpret_cast<const bf16x8*>(Ks + off + 32 * 384);
;     const bf16x8 q = d0 < 8 ? qr[d0 < 8 ? d0 : 0] : qs[(d0 - 8) * 64];
;     p0 = __builtin_amdgcn_mfma_f32_32x32x16_bf16(b0, q, p0, 0, 0, 0);
;     p1 = __builtin_amdgcn_mfma_f32_32x32x16_bf16(b1, q, p1, 0, 0, 0); }
; __device__ __forceinline__ void attn_unit(const bf16* __restrict__ Qb, const bf16* __restrict__ KN, const bf16* __restrict__ KR, ...
;     ...
;   const int sr = tid >> 4, sc = (tid & 15) * 8, vst0 = v_st(sr, sc), vst1 = v_st(32 + sr, sc);
;   const int knd0 = KSWZ(sr, sc * 2), knd1 = knd0 + 32 * 384, krd = KSWZ(tid >> 3, (16 + (tid & 7)) * 16);
;   const int vb0 = (int)(uintptr_t)V_lds + v_rd_base(lane);
;   bf16x8 vs0, vs1, ks0, ks1, ks2;
;     ...
;   f32x16 pA0, pA1, pB0, pB1; float mnA, mnB, alA, alB; bf16x8 pa0, pa1, pa2, pa3; const int NT = seq / KVBLK;
;   SLOAD(0); SWAIT(); SWRITE(0); __syncthreads();
;   qkt(pA0, pA1, K_lds, qr, qs, kb); partialSM(pA0, pA1, m_reg, mnA, alA);
;   SLOAD(KVBLK); SWAIT(); SWRITE(1); __syncthreads();
	v_mfma_f32_32x32x16_bf16 v[32:47], v[68:71], v[116:119], v[32:47]
	v_mul_f32_e64 v68, v144, v110
	v_mul_f32_e64 v69, v144, v111
	v_mul_f32_e64 v56, v56, v68
	v_mul_f32_e64 v57, v57, v69
	v_mul_f32_e64 v68, v144, v112
	v_mul_f32_e64 v69, v144, v113
	v_cvt_pk_bf16_f32 v110, v56, v57
	v_pk_mul_f32 v[56:57], v[144:145], v[124:125] op_sel_hi:[0,1]
	v_pk_mul_f32 v[56:57], v[58:59], v[56:57]
	v_pk_mul_f32 v[52:53], v[52:53], v[68:69]
	v_cvt_pk_bf16_f32 v111, v56, v57
	ds_read_b128 v[56:59], v159 offset:61568
	v_cvt_pk_bf16_f32 v112, v52, v53
	v_pk_mul_f32 v[52:53], v[144:145], v[122:123] op_sel_hi:[0,1]
	v_pk_mul_f32 v[68:69], v[54:55], v[52:53]
	ds_read_b128 v[52:55], v159 offset:61696
	s_waitcnt lgkmcnt(1)
	v_mfma_f32_32x32x16_bf16 v[32:47], v[56:59], v[108:111], v[32:47]
	v_mul_f32_e64 v56, v144, v114
	v_mul_f32_e64 v57, v144, v115
	v_mul_f32_e64 v48, v48, v56
	v_mul_f32_e64 v49, v49, v57
	v_mul_f32_e64 v56, v144, v94
	v_mul_f32_e64 v57, v144, v95
	v_cvt_pk_bf16_f32 v114, v48, v49
	v_pk_mul_f32 v[48:49], v[144:145], v[120:121] op_sel_hi:[0,1]
	v_pk_mul_f32 v[48:49], v[50:51], v[48:49]
	v_pk_mul_f32 v[12:13], v[12:13], v[56:57]
	v_cvt_pk_bf16_f32 v115, v48, v49
	ds_read_b128 v[48:51], v164 offset:61568
	v_mfma_f32_32x32x16_bf16 v[16:31], v[146:149], v[108:111], v[16:31]
	v_cvt_pk_bf16_f32 v113, v68, v69
	v_cvt_pk_bf16_f32 v120, v12, v13
	v_mul_f32_e64 v12, v144, v92
	v_mul_f32_e64 v13, v144, v93
	v_mul_f32_e64 v56, v14, v12
	v_mul_f32_e64 v57, v15, v13
	ds_read_b128 v[12:15], v164 offset:61696
	v_cvt_pk_bf16_f32 v121, v56, v57
	s_mov_b32 s17, s8
	s_waitcnt lgkmcnt(1)
	v_mfma_f32_32x32x16_bf16 v[32:47], v[48:51], v[112:115], v[32:47]
	v_mul_f32_e64 v48, v144, v90
	v_mul_f32_e64 v49, v144, v91
	v_mul_f32_e64 v8, v8, v48
	v_mul_f32_e64 v9, v9, v49
	v_mul_f32_e64 v48, v144, v86
	v_mul_f32_e64 v49, v144, v87
	v_cvt_pk_bf16_f32 v122, v8, v9
	v_pk_mul_f32 v[8:9], v[144:145], v[88:89] op_sel_hi:[0,1]
	v_pk_mul_f32 v[8:9], v[10:11], v[8:9]
	v_pk_mul_f32 v[4:5], v[4:5], v[48:49]
	v_cvt_pk_bf16_f32 v123, v8, v9
	ds_read_b128 v[8:11], v165 offset:61568
	v_mfma_f32_32x32x16_bf16 v[16:31], v[168:171], v[112:115], v[16:31]
	v_cvt_pk_bf16_f32 v124, v4, v5
	v_mul_f32_e64 v4, v144, v84
	v_mul_f32_e64 v5, v144, v85
	v_mul_f32_e64 v48, v6, v4
	v_mul_f32_e64 v49, v7, v5
	ds_read_b128 v[4:7], v165 offset:61696
	v_cvt_pk_bf16_f32 v125, v48, v49
	v_lshl_add_u64 v[164:165], s[46:47], 0, v[136:137]
	s_mov_b32 s18, s8
	v_mfma_f32_32x32x16_bf16 v[16:31], v[150:153], v[120:123], v[16:31]
	s_mov_b32 s19, s8
	s_mov_b32 s20, s8
	s_mov_b32 s21, s8
	s_mov_b32 s22, s8
	s_mov_b32 s23, s8
	s_mov_b32 s48, 2
	s_mov_b32 s49, 1
	s_waitcnt lgkmcnt(1)
	v_mfma_f32_32x32x16_bf16 v[32:47], v[8:11], v[120:123], v[32:47]
	v_mul_f32_e64 v8, v144, v82
	v_mul_f32_e64 v9, v144, v83
	v_mul_f32_e64 v0, v8, v0
	v_mul_f32_e64 v1, v9, v1
	v_cmp_gt_u32_e64 s[4:5], 32, v187
	v_cvt_pk_bf16_f32 v126, v0, v1
	v_pk_mul_f32 v[0:1], v[144:145], v[80:81] op_sel_hi:[0,1]
	v_pk_mul_f32 v[0:1], v[0:1], v[2:3]
	v_mov_b32_e32 v170, 0
	v_cvt_pk_bf16_f32 v127, v0, v1
	ds_read_b128 v[0:3], v130 offset:61568
	ds_read_b128 v[48:51], v130 offset:61696
	v_mfma_f32_32x32x16_bf16 v[16:31], v[64:67], v[124:127], v[16:31]
	s_waitcnt lgkmcnt(1)
	v_mfma_f32_32x32x16_bf16 v[32:47], v[0:3], v[124:127], v[32:47]
	ds_read_b128 v[0:3], v161
	ds_read_b128 v[8:11], v161 offset:1024
	s_waitcnt lgkmcnt(1)
	v_mfma_f32_32x32x16_bf16 v[16:31], v[154:157], v[0:3], v[16:31]
	v_mfma_f32_32x32x16_bf16 v[32:47], v[52:55], v[0:3], v[32:47]
	v_lshl_add_u64 v[0:1], v[162:163], 0, s[2:3]
	v_lshlrev_b64 v[0:1], 11, v[0:1]
	v_lshl_add_u64 v[0:1], s[46:47], 0, v[0:1]
	s_lshl_b64 s[2:3], s[2:3], 7
	v_lshl_add_u64 v[0:1], v[0:1], 0, v[136:137]
	s_add_u32 s2, s26, s2
	v_add_co_u32_e32 v2, vcc, s73, v0
	s_addc_u32 s3, s27, s3
	s_nop 0
	v_addc_co_u32_e32 v3, vcc, 0, v1, vcc
	global_load_dwordx4 v[52:55], v[0:1], off
	global_load_dwordx4 v[56:59], v[0:1], off offset:256
	global_load_dwordx4 v[64:67], v[2:3], off
	global_load_dwordx4 v[68:71], v[2:3], off offset:256
	v_lshl_add_u64 v[0:1], s[2:3], 0, v[140:141]
	global_load_dwordx4 v[76:79], v[0:1], off
	s_waitcnt lgkmcnt(0)
	v_mfma_f32_32x32x16_bf16 v[16:31], v[132:135], v[8:11], v[16:31]
	v_and_b32_e32 v0, 0x3fffffc0, v178
	v_lshl_add_u32 v168, v0, 2, s0
	ds_read_b128 v[0:3], v161 offset:2048
	ds_read_b128 v[80:83], v161 offset:3072
	s_add_i32 s0, 0, 0x12000
	s_waitcnt vmcnt(0)
	s_waitcnt vmcnt(3)
	ds_write_b128 v145, v[56:59] offset:16384
	s_waitcnt vmcnt(1)
	ds_write_b128 v158, v[68:71] offset:16384
	v_mfma_f32_32x32x16_bf16 v[32:47], v[12:15], v[8:11], v[32:47]
	v_lshlrev_b32_e32 v8, 3, v187
	v_and_b32_e32 v9, 0xc0, v166
	v_lshlrev_b32_e32 v10, 1, v187
	v_and_or_b32 v9, v8, 24, v9
	v_and_b32_e32 v10, 32, v10
	v_and_b32_e32 v8, 0x100, v8
	v_or3_b32 v8, v9, v10, v8
	s_waitcnt lgkmcnt(3)
	v_mfma_f32_32x32x16_bf16 v[16:31], v[72:75], v[0:3], v[16:31]
	v_lshl_add_u64 v[166:167], s[26:27], 0, v[140:141]
	v_add_u32_e32 v171, s1, v8
	v_lshl_add_u32 v169, v176, 2, v168
	v_mfma_f32_32x32x16_bf16 v[32:47], v[4:7], v[0:3], v[32:47]
	v_mov_b64_e32 v[0:1], s[8:9]
	v_mov_b64_e32 v[14:15], s[22:23]
	v_mov_b64_e32 v[2:3], s[10:11]
	v_mov_b64_e32 v[4:5], s[12:13]
	v_mov_b64_e32 v[6:7], s[14:15]
	v_mov_b64_e32 v[8:9], s[16:17]
	v_mov_b64_e32 v[10:11], s[18:19]
	s_waitcnt lgkmcnt(2)
; #define SBAR() __builtin_amdgcn_sched_barrier(0)
; #define SLOAD(k0) do { const long rb = KROW(k0); const bf16* pn = KN + (rb + sr) * LDKN + sc; \
;     ks0 = *reinterpret_cast<const bf16x8*>(pn); ks1 = *reinterpret_cast<const bf16x8*>(pn + 32 * LDKN); vs0 = *reinterpret_cast<const bf16x8*>(pn + 128); vs1 = *reinterpret_cast<const bf16x8*>(pn + 32 * LDKN + 128); \
;     ks2 = *reinterpret_cast<const bf16x8*>(KR + rb * LDKR + tid * 8); } while (0)
; #define SWRITE(b) do { *(bf16x8*)(V_lds + (b) * SHM_V + vst0) = vs0; *(bf16x8*)(V_lds + (b) * SHM_V + vst1) = vs1; \
;     *(bf16x8*)(K_lds + (b) * SHM_K + knd0) = ks0; *(bf16x8*)(K_lds + (b) * SHM_K + knd1) = ks1; *(bf16x8*)(K_lds + (b) * SHM_K + krd) = ks2; } while (0)
; #define SWAIT() asm volatile("s_waitcnt vmcnt(0)" ::: "memory")
; __device__ __forceinline__ void partialSM(f32x16& p0, f32x16& p1, float& m_reg, float& mn, float& alpha) {
;   constexpr float C = SCALE * 1.4426950408889634f;
;   float pmax = p0[0]; for (int r = 1; r < 16; ++r) pmax = fmaxf(pmax, p0[r]); for (int r = 0; r < 16; ++r) pmax = fmaxf(pmax, p1[r]);
;   { auto rr = __builtin_amdgcn_permlane32_swap(__float_as_uint(pmax), __float_as_uint(pmax), false, false);
;     pmax = fmaxf(__uint_as_float(rr[0]), __uint_as_float(rr[1])); }
;   if (__builtin_expect(__all(pmax - m_reg <= THR / SCALE), 1)) { mn = m_reg; alpha = 1.f; }
;   else { mn = fmaxf(m_reg, pmax); alpha = __builtin_amdgcn_exp2f((m_reg - mn) * C); m_reg = mn; }
;   float mnC = -mn * C;
;   for (int r = 0; r < 16; ++r) p0[r] = fmaf(p0[r], C, mnC); for (int r = 0; r < 16; ++r) p1[r] = fmaf(p1[r], C, mnC);
;   for (int r = 0; r < 16; ++r) p0[r] = __builtin_amdgcn_exp2f(p0[r]);
; }
; __device__ __forceinline__ void attn_unit(const bf16* __restrict__ Qb, const bf16* __restrict__ KN, const bf16* __restrict__ KR, ...
;     ...
;   f32x16 pA0, pA1, pB0, pB1; float mnA, mnB, alA, alB; bf16x8 pa0, pa1, pa2, pa3; const int NT = seq / KVBLK;
;   SLOAD(0); SWAIT(); SWRITE(0); __syncthreads();
;   qkt(pA0, pA1, K_lds, qr, qs, kb); partialSM(pA0, pA1, m_reg, mnA, alA);
;   SLOAD(KVBLK); SWAIT(); SWRITE(1); __syncthreads();
;   int rp = 0, rc = 1, rn = 2;
;   for (int j = 1; j + 1 < NT; j += 2) {
;     SBAR(); qkt(pB0, pB1, K_lds + rc * SHM_K, qr, qs, kb);
	v_mfma_f32_32x32x16_bf16 v[16:31], v[60:63], v[80:83], v[16:31]
	v_mov_b64_e32 v[12:13], s[20:21]
	s_mov_b64 s[10:11], 0x80
	v_mfma_f32_32x32x16_bf16 v[32:47], v[48:51], v[80:83], v[32:47]
	s_nop 8
	v_max_f32_e32 v48, v17, v17
	v_max_f32_e32 v49, v16, v16
	v_max_f32_e32 v48, v49, v48
	v_max3_f32 v48, v48, v18, v19
	v_max3_f32 v48, v48, v20, v21
	v_max3_f32 v48, v48, v22, v23
	v_max3_f32 v48, v48, v24, v25
	v_max3_f32 v48, v48, v26, v27
	v_max3_f32 v48, v48, v28, v29
	v_max3_f32 v48, v48, v30, v31
	v_max3_f32 v48, v48, v32, v33
	v_max3_f32 v48, v48, v34, v35
	v_max3_f32 v48, v48, v36, v37
	v_max3_f32 v48, v48, v38, v39
	v_max3_f32 v48, v48, v40, v41
	v_max3_f32 v48, v48, v42, v43
	v_max3_f32 v48, v48, v44, v45
	v_max3_f32 v48, v48, v46, v47
	v_mov_b32_e32 v49, v48
	s_nop 1
	v_permlane32_swap_b32_e32 v48, v49
	v_max_f32_e32 v49, v49, v49
	v_max_f32_e32 v48, v48, v48
	v_max_f32_e32 v48, v48, v49
	v_add_f32_e32 v49, 0x7149f2ca, v48
	v_cmp_ge_f32_e32 vcc, s74, v49
	v_add_u32_e32 v49, s0, v179
	ds_write_b128 v49, v[52:55]
	ds_write_b128 v49, v[64:67] offset:12288
	v_add_u32_e32 v49, s0, v180
	s_cmp_eq_u64 vcc, exec
	s_waitcnt vmcnt(0)
	ds_write_b128 v49, v[76:79]
	v_max_f32_e32 v49, 0xf149f2ca, v48
	s_cselect_b64 vcc, -1, 0
	v_mov_b32_e32 v48, 0xf149f2ca
	v_cndmask_b32_e32 v178, v49, v48, vcc
	v_mul_f32_e32 v48, 0xbdd53b94, v178
	v_fmamk_f32 v16, v16, 0x3dd53b94, v48
	v_exp_f32_e32 v149, v16
	v_fmamk_f32 v16, v17, 0x3dd53b94, v48
	v_exp_f32_e32 v150, v16
	v_fmamk_f32 v16, v18, 0x3dd53b94, v48
	v_exp_f32_e32 v151, v16
	v_fmamk_f32 v16, v19, 0x3dd53b94, v48
	v_exp_f32_e32 v157, v16
	v_fmamk_f32 v16, v20, 0x3dd53b94, v48
	v_exp_f32_e32 v159, v16
	v_fmamk_f32 v16, v21, 0x3dd53b94, v48
	v_exp_f32_e32 v188, v16
	v_fmamk_f32 v16, v22, 0x3dd53b94, v48
	v_exp_f32_e32 v152, v16
	v_fmamk_f32 v16, v23, 0x3dd53b94, v48
	v_exp_f32_e32 v158, v16
	v_fmamk_f32 v16, v24, 0x3dd53b94, v48
	v_exp_f32_e32 v144, v16
	v_fmamk_f32 v16, v25, 0x3dd53b94, v48
	v_exp_f32_e32 v146, v16
	v_fmamk_f32 v16, v26, 0x3dd53b94, v48
	v_pk_fma_f32 v[136:137], v[38:39], s[68:69], v[48:49] op_sel_hi:[1,0,0]
	v_sub_f32_e32 v38, 0xf149f2ca, v49
	v_exp_f32_e32 v153, v16
	v_fmamk_f32 v16, v27, 0x3dd53b94, v48
	v_mul_f32_e32 v38, 0x3dd53b94, v38
	v_exp_f32_e32 v154, v16
	v_fmamk_f32 v16, v28, 0x3dd53b94, v48
	v_exp_f32_e32 v38, v38
	v_exp_f32_e32 v145, v16
	v_fmamk_f32 v16, v29, 0x3dd53b94, v48
	v_pk_fma_f32 v[128:129], v[46:47], s[68:69], v[48:49] op_sel_hi:[1,0,0]
	v_pk_fma_f32 v[130:131], v[44:45], s[68:69], v[48:49] op_sel_hi:[1,0,0]
	v_pk_fma_f32 v[132:133], v[42:43], s[68:69], v[48:49] op_sel_hi:[1,0,0]
	v_pk_fma_f32 v[134:135], v[40:41], s[68:69], v[48:49] op_sel_hi:[1,0,0]
	v_pk_fma_f32 v[138:139], v[36:37], s[68:69], v[48:49] op_sel_hi:[1,0,0]
	v_pk_fma_f32 v[140:141], v[34:35], s[68:69], v[48:49] op_sel_hi:[1,0,0]
	v_pk_fma_f32 v[142:143], v[32:33], s[68:69], v[48:49] op_sel_hi:[1,0,0]
	v_exp_f32_e32 v147, v16
	v_fmamk_f32 v16, v30, 0x3dd53b94, v48
	v_fmac_f32_e32 v48, 0x3dd53b94, v31
	v_exp_f32_e32 v155, v16
	v_exp_f32_e32 v156, v48
	v_cndmask_b32_e64 v184, v38, 1.0, vcc
	v_mov_b64_e32 v[62:63], v[14:15]
	v_mov_b64_e32 v[46:47], v[14:15]
	v_mov_b64_e32 v[30:31], v[14:15]
	v_mov_b64_e32 v[60:61], v[12:13]
	v_mov_b64_e32 v[58:59], v[10:11]
	v_mov_b64_e32 v[56:57], v[8:9]
	v_mov_b64_e32 v[54:55], v[6:7]
	v_mov_b64_e32 v[52:53], v[4:5]
	v_mov_b64_e32 v[50:51], v[2:3]
	v_mov_b64_e32 v[48:49], v[0:1]
	v_mov_b64_e32 v[44:45], v[12:13]
	v_mov_b64_e32 v[42:43], v[10:11]
	v_mov_b64_e32 v[40:41], v[8:9]
	v_mov_b64_e32 v[38:39], v[6:7]
	v_mov_b64_e32 v[36:37], v[4:5]
	v_mov_b64_e32 v[34:35], v[2:3]
	v_mov_b64_e32 v[32:33], v[0:1]
	v_mov_b64_e32 v[28:29], v[12:13]
	v_mov_b64_e32 v[26:27], v[10:11]
	v_mov_b64_e32 v[24:25], v[8:9]
	v_mov_b64_e32 v[22:23], v[6:7]
	v_mov_b64_e32 v[20:21], v[4:5]
	v_mov_b64_e32 v[18:19], v[2:3]
	v_mov_b64_e32 v[16:17], v[0:1]
	s_mov_b32 s0, 2
	s_waitcnt lgkmcnt(0)
	s_barrier
	s_mov_b32 s9, s0
	v_mov_b32_e32 v249, v184
	ds_read_b128 v[226:229], v161 offset:0
	ds_read_b128 v[230:233], v161 offset:1024
	ds_read_b128 v[234:237], v161 offset:2048
	ds_read_b128 v[238:241], v161 offset:3072
	v_mov_b32_e32 v80, v149
	v_mov_b32_e32 v81, v150
	v_mov_b32_e32 v82, v151
	v_mov_b32_e32 v83, v157
	v_mov_b32_e32 v84, v159
	v_mov_b32_e32 v85, v188
	v_mov_b32_e32 v86, v152
	v_mov_b32_e32 v87, v158
	v_mov_b32_e32 v88, v144
	v_mov_b32_e32 v89, v146
	v_mov_b32_e32 v90, v153
	v_mov_b32_e32 v91, v154
	v_mov_b32_e32 v92, v145
	v_mov_b32_e32 v93, v147
	v_mov_b32_e32 v94, v155
	v_mov_b32_e32 v95, v156
	v_mov_b32_e32 v64, v142
	v_mov_b32_e32 v65, v143
	v_mov_b32_e32 v66, v140
	v_mov_b32_e32 v67, v141
	v_mov_b32_e32 v68, v138
	v_mov_b32_e32 v69, v139
	v_mov_b32_e32 v70, v136
	v_mov_b32_e32 v71, v137
	v_mov_b32_e32 v72, v134
	v_mov_b32_e32 v73, v135
	v_mov_b32_e32 v74, v132
	v_mov_b32_e32 v75, v133
	v_mov_b32_e32 v76, v130
	v_mov_b32_e32 v77, v131
	v_mov_b32_e32 v78, v128
	v_mov_b32_e32 v79, v129
	s_waitcnt lgkmcnt(0)
; __device__ __forceinline__ void finishSM(f32x16& p0, f32x16& p1, float alpha, float& l_reg, bf16x8& pa0, bf16x8& pa1, bf16x8& pa2, bf16x8& pa3) {
;   for (int r = 0; r < 16; ++r) p1[r] = __builtin_amdgcn_exp2f(p1[r]);
;   float ps = 0; for (int r = 0; r < 16; ++r) ps += p0[r]; for (int r = 0; r < 16; ++r) ps += p1[r];
;   { auto rr = __builtin_amdgcn_permlane32_swap(__float_as_uint(ps), __float_as_uint(ps), false, false);
;     ps = __uint_as_float(rr[0]) + __uint_as_float(rr[1]); }
;   l_reg = l_reg * alpha + ps;
;     ...
;   PK4(p0, 0, pa0); PK4(p0, 8, pa1); PK4(p1, 0, pa2); PK4(p1, 8, pa3);
;     ...
; }
; __device__ __forceinline__ void qkt(f32x16& p0, f32x16& p1, const char* Ks, const bf16x8* qr, const bf16x8* qs, const int* kb) {
;   p0 = f32x16{}; p1 = f32x16{};
; #pragma unroll
;   for (int d0 = 0; d0 < 12; ++d0) { const int off = kb[d0 & 3] + (d0 >> 2) * 128;
;     bf16x8 b0 = *reinterpret_cast<const bf16x8*>(Ks + off);
;     bf16x8 b1 = *reinterpret_cast<const bf16x8*>(Ks + off + 32 * 384);
;     const bf16x8 q = d0 < 8 ? qr[d0 < 8 ? d0 : 0] : qs[(d0 - 8) * 64];
;     p0 = __builtin_amdgcn_mfma_f32_32x32x16_bf16(b0, q, p0, 0, 0, 0);
;     p1 = __builtin_amdgcn_mfma_f32_32x32x16_bf16(b1, q, p1, 0, 0, 0); }
.LBB0_107:
	s_mul_i32 s0, s49, 0x6000
	v_add_u32_e32 v250, s0, v173
	v_add_u32_e32 v251, s0, v181
	v_add_u32_e32 v252, s0, v182
	v_add_u32_e32 v172, s0, v183
	v_lshl_add_u32 v246, s8, 14, v171
	ds_read_b128 v[210:213], v250 offset:49152
	ds_read_b128 v[214:217], v250 offset:61440
	ds_read_b128 v[218:221], v251 offset:49152
	ds_read_b128 v[222:225], v251 offset:61440
	ds_read_b128 v[204:207], v252 offset:49152
	ds_read_b128 v[184:187], v252 offset:61440
	v_cvt_pk_bf16_f32 v188, v80, v81
	v_cvt_pk_bf16_f32 v189, v82, v83
	v_cvt_pk_bf16_f32 v190, v84, v85
	v_cvt_pk_bf16_f32 v191, v86, v87
	v_exp_f32_e32 v64, v64
	v_exp_f32_e32 v65, v65
	v_exp_f32_e32 v66, v66
	v_exp_f32_e32 v67, v67
	s_waitcnt lgkmcnt(5)
	v_mfma_f32_32x32x16_bf16 v[144:159], v[210:213], v[96:99], 0
	v_permlane32_swap_b32_e32 v188, v190
	v_permlane32_swap_b32_e32 v189, v191
	v_cvt_pk_bf16_f32 v192, v88, v89
	v_cvt_pk_bf16_f32 v193, v90, v91
	s_waitcnt lgkmcnt(4)
	v_mfma_f32_32x32x16_bf16 v[128:143], v[214:217], v[96:99], 0
	ds_read_b128 v[210:213], v172 offset:49152
	ds_read_b128 v[214:217], v172 offset:61440
	v_cvt_pk_bf16_f32 v194, v92, v93
	v_cvt_pk_bf16_f32 v195, v94, v95
	v_exp_f32_e32 v68, v68
	s_waitcnt lgkmcnt(5)
	v_mfma_f32_32x32x16_bf16 v[144:159], v[218:221], v[100:103], v[144:159]
	v_exp_f32_e32 v69, v69
	v_exp_f32_e32 v70, v70
	s_waitcnt lgkmcnt(4)
	v_mfma_f32_32x32x16_bf16 v[128:143], v[222:225], v[100:103], v[128:143]
	ds_read_b128 v[218:221], v250 offset:49280
	ds_read_b128 v[222:225], v250 offset:61568
	v_exp_f32_e32 v71, v71
	v_permlane32_swap_b32_e32 v192, v194
	s_waitcnt lgkmcnt(5)
	v_mfma_f32_32x32x16_bf16 v[144:159], v[204:207], v[104:107], v[144:159]
	v_permlane32_swap_b32_e32 v193, v195
	v_add_f32_e32 v255, v80, v81
	v_add_f32_e32 v255, v82, v255
	s_waitcnt lgkmcnt(4)
	v_mfma_f32_32x32x16_bf16 v[128:143], v[184:187], v[104:107], v[128:143]
	ds_read_b128 v[204:207], v251 offset:49280
	ds_read_b128 v[184:187], v251 offset:61568
	v_exp_f32_e32 v72, v72
	v_add_f32_e32 v255, v83, v255
	v_add_f32_e32 v255, v84, v255
	s_waitcnt lgkmcnt(5)
	v_mfma_f32_32x32x16_bf16 v[144:159], v[210:213], v[116:119], v[144:159]
	v_exp_f32_e32 v73, v73
	v_add_f32_e32 v255, v85, v255
	v_add_f32_e32 v255, v86, v255
	s_waitcnt lgkmcnt(4)
	v_mfma_f32_32x32x16_bf16 v[128:143], v[214:217], v[116:119], v[128:143]
	ds_read_b128 v[210:213], v252 offset:49280
	ds_read_b128 v[214:217], v252 offset:61568
	v_exp_f32_e32 v74, v74
	v_add_f32_e32 v255, v87, v255
	s_waitcnt lgkmcnt(5)
	v_mfma_f32_32x32x16_bf16 v[144:159], v[218:221], v[108:111], v[144:159]
	v_add_f32_e32 v255, v88, v255
	v_exp_f32_e32 v75, v75
	v_add_f32_e32 v255, v89, v255
	s_waitcnt lgkmcnt(4)
	v_mfma_f32_32x32x16_bf16 v[128:143], v[222:225], v[108:111], v[128:143]
	ds_read_b128 v[218:221], v172 offset:49280
	ds_read_b128 v[222:225], v172 offset:61568
	v_add_f32_e32 v255, v90, v255
	v_exp_f32_e32 v76, v76
	s_waitcnt lgkmcnt(5)
	v_mfma_f32_32x32x16_bf16 v[144:159], v[204:207], v[112:115], v[144:159]
	v_add_f32_e32 v255, v91, v255
	v_add_f32_e32 v255, v92, v255
	v_exp_f32_e32 v77, v77
	s_waitcnt lgkmcnt(4)
	v_mfma_f32_32x32x16_bf16 v[128:143], v[184:187], v[112:115], v[128:143]
	ds_read_b128 v[204:207], v250 offset:49408
	ds_read_b128 v[184:187], v250 offset:61696
	v_add_f32_e32 v255, v93, v255
	v_add_f32_e32 v255, v94, v255
	v_exp_f32_e32 v78, v78
	s_waitcnt lgkmcnt(5)
	v_mfma_f32_32x32x16_bf16 v[144:159], v[210:213], v[120:123], v[144:159]
	v_add_f32_e32 v255, v95, v255
	v_exp_f32_e32 v79, v79
	s_waitcnt lgkmcnt(4)
	v_mfma_f32_32x32x16_bf16 v[128:143], v[214:217], v[120:123], v[128:143]
	ds_read_b128 v[210:213], v251 offset:49408
	ds_read_b128 v[214:217], v251 offset:61696
	v_cvt_pk_bf16_f32 v196, v64, v65
	v_cvt_pk_bf16_f32 v197, v66, v67
	v_cvt_pk_bf16_f32 v198, v68, v69
	v_cvt_pk_bf16_f32 v199, v70, v71
	s_waitcnt lgkmcnt(5)
	v_mfma_f32_32x32x16_bf16 v[144:159], v[218:221], v[124:127], v[144:159]
	v_add_f32_e32 v203, v64, v65
	v_add_f32_e32 v203, v66, v203
	v_add_f32_e32 v203, v67, v203
	s_waitcnt lgkmcnt(4)
	v_mfma_f32_32x32x16_bf16 v[128:143], v[222:225], v[124:127], v[128:143]
	ds_read_b128 v[218:221], v252 offset:49408
	ds_read_b128 v[222:225], v252 offset:61696
	v_add_f32_e32 v203, v68, v203
	v_add_f32_e32 v203, v69, v203
	v_add_f32_e32 v203, v70, v203
	v_add_f32_e32 v203, v71, v203
	s_waitcnt lgkmcnt(5)
	v_mfma_f32_32x32x16_bf16 v[144:159], v[204:207], v[226:229], v[144:159]
	v_add_f32_e32 v203, v72, v203
	v_permlane32_swap_b32_e32 v196, v198
	v_permlane32_swap_b32_e32 v197, v199
	v_add_f32_e32 v203, v73, v203
	s_waitcnt lgkmcnt(4)
	v_mfma_f32_32x32x16_bf16 v[128:143], v[184:187], v[226:229], v[128:143]
	ds_read_b128 v[204:207], v172 offset:49408
	ds_read_b128 v[184:187], v172 offset:61696
	v_add_f32_e32 v203, v74, v203
	v_add_f32_e32 v203, v75, v203
	v_add_f32_e32 v203, v76, v203
	s_waitcnt lgkmcnt(5)
	v_mfma_f32_32x32x16_bf16 v[144:159], v[210:213], v[230:233], v[144:159]
	v_add_f32_e32 v203, v77, v203
	v_add_f32_e32 v203, v78, v203
	v_add_f32_e32 v203, v79, v203
	v_add_f32_e32 v255, v255, v203
	s_waitcnt lgkmcnt(4)
	v_mfma_f32_32x32x16_bf16 v[128:143], v[214:217], v[230:233], v[128:143]
	ds_read_b64_tr_b16 v[210:211], v246 offset:0
	ds_read_b64_tr_b16 v[212:213], v246 offset:2048
	ds_read_b64_tr_b16 v[214:215], v246 offset:4096
	ds_read_b64_tr_b16 v[216:217], v246 offset:6144
	v_mov_b32_e32 v202, v255
	s_nop 1
	v_permlane32_swap_b32_e32 v255, v202
	v_add_f32_e32 v255, v255, v202
	s_waitcnt lgkmcnt(7)
	v_mfma_f32_32x32x16_bf16 v[144:159], v[218:221], v[234:237], v[144:159]
	v_fma_f32 v170, v170, v249, v255
	v_cvt_pk_bf16_f32 v200, v72, v73
	v_cvt_pk_bf16_f32 v201, v74, v75
	v_cvt_pk_bf16_f32 v202, v76, v77
	s_waitcnt lgkmcnt(6)
; #define PV_WAIT(n, f) asm volatile("s_waitcnt lgkmcnt(" #n ")" : "+v"(f[0]), "+v"(f[1]), "+v"(f[2]), "+v"(f[3]), "+v"(f[4]), "+v"(f[5]), "+v"(f[6]), "+v"(f[7]))
; __device__ __forceinline__ void partialSM(f32x16& p0, f32x16& p1, float& m_reg, float& mn, float& alpha) {
;   constexpr float C = SCALE * 1.4426950408889634f;
;   float pmax = p0[0]; for (int r = 1; r < 16; ++r) pmax = fmaxf(pmax, p0[r]); for (int r = 0; r < 16; ++r) pmax = fmaxf(pmax, p1[r]);
;   { auto rr = __builtin_amdgcn_permlane32_swap(__float_as_uint(pmax), __float_as_uint(pmax), false, false);
;     pmax = fmaxf(__uint_as_float(rr[0]), __uint_as_float(rr[1])); }
;   if (__builtin_expect(__all(pmax - m_reg <= THR / SCALE), 1)) { mn = m_reg; alpha = 1.f; }
;   else { mn = fmaxf(m_reg, pmax); alpha = __builtin_amdgcn_exp2f((m_reg - mn) * C); m_reg = mn; }
;   float mnC = -mn * C;
;   for (int r = 0; r < 16; ++r) p0[r] = fmaf(p0[r], C, mnC); for (int r = 0; r < 16; ++r) p1[r] = fmaf(p1[r], C, mnC);
;   for (int r = 0; r < 16; ++r) p0[r] = __builtin_amdgcn_exp2f(p0[r]);
; }
; __device__ __forceinline__ void pv_d0(f32x16* o, int vb, bf16x8 pa0, bf16x8 pa1, bf16x8 pa2, bf16x8 pa3) {
;   s16x4 fa[8], fb[8];
;   pv_rd<0>(fa, vb); pv_rd<1>(fb, vb);
;   PV_WAIT(8, fa); pv_mm(o[0], fa, pa0, pa1, pa2, pa3);
;   pv_rd<2>(fa, vb);
;   PV_WAIT(8, fb); pv_mm(o[1], fb, pa0, pa1, pa2, pa3);
;   pv_rd<3>(fb, vb);
;   PV_WAIT(8, fa); pv_mm(o[2], fa, pa0, pa1, pa2, pa3);
;   PV_WAIT(0, fb); pv_mm(o[3], fb, pa0, pa1, pa2, pa3);
; }
	v_mfma_f32_32x32x16_bf16 v[128:143], v[222:225], v[234:237], v[128:143]
	ds_read_b64_tr_b16 v[218:219], v246 offset:8192
	ds_read_b64_tr_b16 v[220:221], v246 offset:10240
	ds_read_b64_tr_b16 v[222:223], v246 offset:12288
	ds_read_b64_tr_b16 v[224:225], v246 offset:14336
	v_cvt_pk_bf16_f32 v203, v78, v79
	v_permlane32_swap_b32_e32 v200, v202
	s_nop 0
	v_permlane32_swap_b32_e32 v201, v203
	s_waitcnt lgkmcnt(9)
	v_mfma_f32_32x32x16_bf16 v[144:159], v[204:207], v[238:241], v[144:159]
	s_waitcnt lgkmcnt(8)
	v_mfma_f32_32x32x16_bf16 v[128:143], v[184:187], v[238:241], v[128:143]
	ds_read_b64_tr_b16 v[204:205], v246 offset:512
	ds_read_b64_tr_b16 v[206:207], v246 offset:2560
	ds_read_b64_tr_b16 v[184:185], v246 offset:4608
	ds_read_b64_tr_b16 v[186:187], v246 offset:6656
	s_cmp_lt_u32 s10, s42
	s_cselect_b32 s0, s44, s45
	s_ashr_i32 s1, s0, 31
	s_add_u32 s0, s10, s0
	s_addc_u32 s1, s11, s1
	v_lshl_add_u64 v[64:65], s[0:1], 0, v[162:163]
	v_lshlrev_b64 v[64:65], 11, v[64:65]
	v_lshl_add_u64 v[68:69], v[164:165], 0, v[64:65]
	v_add_co_u32_e32 v72, vcc, s73, v68
	s_lshl_b64 s[0:1], s[0:1], 7
	s_nop 0
	v_addc_co_u32_e32 v73, vcc, 0, v69, vcc
	global_load_dwordx4 v[64:67], v[68:69], off
	global_load_dwordx4 v[76:79], v[68:69], off offset:256
	s_nop 0
	global_load_dwordx4 v[68:71], v[72:73], off
	global_load_dwordx4 v[80:83], v[72:73], off offset:256
	v_lshl_add_u64 v[72:73], v[166:167], 0, s[0:1]
	global_load_dwordx4 v[72:75], v[72:73], off
	s_lshl_b32 s14, s9, 14
	s_lshl_b32 s1, s9, 13
	s_add_i32 s15, s14, s1
	s_waitcnt lgkmcnt(10)
	v_mfma_f32_32x32x16_bf16 v[0:15], v[188:191], v[210:213], v[0:15]
	ds_read_b64_tr_b16 v[210:211], v246 offset:8704
	ds_read_b64_tr_b16 v[212:213], v246 offset:10752
	v_max3_f32 v84, v144, v145, v146
	v_max3_f32 v85, v128, v129, v130
	v_max3_f32 v84, v84, v147, v148
	v_max3_f32 v85, v85, v131, v132
	v_max3_f32 v84, v84, v149, v150
	v_max3_f32 v85, v85, v133, v134
	s_waitcnt lgkmcnt(10)
	v_mfma_f32_32x32x16_bf16 v[0:15], v[192:195], v[214:217], v[0:15]
	ds_read_b64_tr_b16 v[214:215], v246 offset:12800
	ds_read_b64_tr_b16 v[216:217], v246 offset:14848
	v_max3_f32 v84, v84, v151, v152
	v_max3_f32 v85, v85, v135, v136
	v_max3_f32 v84, v84, v153, v154
	v_max3_f32 v85, v85, v137, v138
	v_max3_f32 v84, v84, v155, v156
	v_max3_f32 v85, v85, v139, v140
	s_waitcnt lgkmcnt(10)
	v_mfma_f32_32x32x16_bf16 v[0:15], v[196:199], v[218:221], v[0:15]
	ds_read_b64_tr_b16 v[218:219], v246 offset:1024
	ds_read_b64_tr_b16 v[220:221], v246 offset:3072
	v_max3_f32 v84, v84, v157, v158
	v_max3_f32 v85, v85, v141, v142
	v_max_f32_e32 v84, v84, v159
	v_max_f32_e32 v85, v85, v143
	v_max_f32_e32 v84, v84, v85
	v_mov_b32_e32 v86, v84
	s_waitcnt lgkmcnt(10)
	v_mfma_f32_32x32x16_bf16 v[0:15], v[200:203], v[222:225], v[0:15]
	ds_read_b64_tr_b16 v[222:223], v246 offset:5120
	ds_read_b64_tr_b16 v[224:225], v246 offset:7168
	v_permlane32_swap_b32_e32 v84, v86
	v_max_f32_e32 v84, v84, v86
	v_sub_f32_e32 v87, v84, v178
	v_cmp_ge_f32_e32 vcc, s74, v87
	v_max_f32_e32 v88, v178, v84
	v_sub_f32_e32 v87, v178, v88
	s_waitcnt lgkmcnt(10)
	v_mfma_f32_32x32x16_bf16 v[48:63], v[188:191], v[204:207], v[48:63]
	ds_read_b64_tr_b16 v[204:205], v246 offset:9216
	ds_read_b64_tr_b16 v[206:207], v246 offset:11264
	v_mul_f32_e32 v87, 0x3dd53b94, v87
	v_exp_f32_e32 v87, v87
	s_cmp_eq_u64 vcc, exec
	s_cselect_b64 s[6:7], -1, 0
	v_cndmask_b32_e64 v249, v87, 1.0, s[6:7]
	v_cndmask_b32_e64 v178, v88, v178, s[6:7]
	s_waitcnt lgkmcnt(10)
	v_mfma_f32_32x32x16_bf16 v[48:63], v[192:195], v[184:187], v[48:63]
	ds_read_b64_tr_b16 v[184:185], v246 offset:13312
	ds_read_b64_tr_b16 v[186:187], v246 offset:15360
	v_mul_f32_e32 v89, 0xbdd53b94, v178
	v_cmp_gt_f32_e32 vcc, 1.0, v249
	v_fmamk_f32 v144, v144, 0x3dd53b94, v89
	v_fmamk_f32 v145, v145, 0x3dd53b94, v89
	v_fmamk_f32 v146, v146, 0x3dd53b94, v89
	v_fmamk_f32 v147, v147, 0x3dd53b94, v89
	s_waitcnt lgkmcnt(10)
	v_mfma_f32_32x32x16_bf16 v[48:63], v[196:199], v[210:213], v[48:63]
	ds_read_b64_tr_b16 v[210:211], v246 offset:1536
	ds_read_b64_tr_b16 v[212:213], v246 offset:3584
	v_fmamk_f32 v148, v148, 0x3dd53b94, v89
	v_fmamk_f32 v149, v149, 0x3dd53b94, v89
	v_fmamk_f32 v150, v150, 0x3dd53b94, v89
	v_fmamk_f32 v151, v151, 0x3dd53b94, v89
	v_fmamk_f32 v152, v152, 0x3dd53b94, v89
	v_exp_f32_e32 v144, v144
	s_waitcnt lgkmcnt(10)
	v_mfma_f32_32x32x16_bf16 v[48:63], v[200:203], v[214:217], v[48:63]
	ds_read_b64_tr_b16 v[214:215], v246 offset:5632
	ds_read_b64_tr_b16 v[216:217], v246 offset:7680
	v_fmamk_f32 v153, v153, 0x3dd53b94, v89
	v_exp_f32_e32 v145, v145
	v_fmamk_f32 v154, v154, 0x3dd53b94, v89
	v_exp_f32_e32 v146, v146
	s_waitcnt lgkmcnt(10)
	v_mfma_f32_32x32x16_bf16 v[32:47], v[188:191], v[218:221], v[32:47]
	ds_read_b64_tr_b16 v[218:219], v246 offset:9728
	ds_read_b64_tr_b16 v[220:221], v246 offset:11776
	v_fmamk_f32 v155, v155, 0x3dd53b94, v89
	v_exp_f32_e32 v147, v147
	v_fmamk_f32 v156, v156, 0x3dd53b94, v89
	v_exp_f32_e32 v148, v148
	s_waitcnt lgkmcnt(10)
	v_mfma_f32_32x32x16_bf16 v[32:47], v[192:195], v[222:225], v[32:47]
	ds_read_b64_tr_b16 v[222:223], v246 offset:13824
	ds_read_b64_tr_b16 v[224:225], v246 offset:15872
	v_fmamk_f32 v157, v157, 0x3dd53b94, v89
	v_exp_f32_e32 v149, v149
	v_fmamk_f32 v158, v158, 0x3dd53b94, v89
	v_exp_f32_e32 v150, v150
	s_waitcnt lgkmcnt(10)
	v_mfma_f32_32x32x16_bf16 v[32:47], v[196:199], v[204:207], v[32:47]
	v_fmamk_f32 v159, v159, 0x3dd53b94, v89
	v_exp_f32_e32 v151, v151
	v_fmamk_f32 v128, v128, 0x3dd53b94, v89
	v_fmamk_f32 v129, v129, 0x3dd53b94, v89
	s_waitcnt lgkmcnt(8)
; #define SBAR() __builtin_amdgcn_sched_barrier(0)
; #define SWRITE(b) do { *(bf16x8*)(V_lds + (b) * SHM_V + vst0) = vs0; *(bf16x8*)(V_lds + (b) * SHM_V + vst1) = vs1; \
;     *(bf16x8*)(K_lds + (b) * SHM_K + knd0) = ks0; *(bf16x8*)(K_lds + (b) * SHM_K + knd1) = ks1; *(bf16x8*)(K_lds + (b) * SHM_K + krd) = ks2; } while (0)
; #define RESC(a) do { if (__any((a) < 1.f)) { if (hi == 0) al_l[r32] = (a); asm volatile("s_waitcnt lgkmcnt(0)" ::: "memory"); \
;     for (int d = 0; d < 4; ++d) for (int r = 0; r < 16; ++r) o[d][r] *= al_l[crow(r, hi)]; } } while (0)
; __device__ __forceinline__ void attn_unit(const bf16* __restrict__ Qb, const bf16* __restrict__ KN, const bf16* __restrict__ KR, ...
;     ...
;     pv_d0(o, vb0 + rp * SHM_V, pa0, pa1, pa2, pa3); partialSM(pB0, pB1, m_reg, mnB, alB);
;     SWRITE(rn);
;     RESC(alB); __syncthreads();
;     { const int t = rp; rp = rc; rc = rn; rn = t; }
;     SBAR(); qkt(pA0, pA1, K_lds + rc * SHM_K, qr, qs, kb);
;     finishSM(pB0, pB1, alB, l_reg, pa0, pa1, pa2, pa3); SBAR();
	v_mfma_f32_32x32x16_bf16 v[32:47], v[200:203], v[184:187], v[32:47]
	v_exp_f32_e32 v152, v152
	v_fmamk_f32 v130, v130, 0x3dd53b94, v89
	v_fmamk_f32 v131, v131, 0x3dd53b94, v89
	v_exp_f32_e32 v153, v153
	v_add_u32_e32 v90, s14, v174
	s_waitcnt vmcnt(3)
	ds_write_b128 v90, v[76:79]
	s_waitcnt lgkmcnt(7)
	v_mfma_f32_32x32x16_bf16 v[16:31], v[188:191], v[210:213], v[16:31]
	v_fmamk_f32 v132, v132, 0x3dd53b94, v89
	v_fmamk_f32 v133, v133, 0x3dd53b94, v89
	v_exp_f32_e32 v154, v154
	v_fmamk_f32 v134, v134, 0x3dd53b94, v89
	v_fmamk_f32 v135, v135, 0x3dd53b94, v89
	v_add_u32_e32 v91, s14, v175
	s_waitcnt vmcnt(1)
	ds_write_b128 v91, v[80:83]
	s_waitcnt lgkmcnt(6)
	v_mfma_f32_32x32x16_bf16 v[16:31], v[192:195], v[214:217], v[16:31]
	v_exp_f32_e32 v155, v155
	v_fmamk_f32 v136, v136, 0x3dd53b94, v89
	v_fmamk_f32 v137, v137, 0x3dd53b94, v89
	v_exp_f32_e32 v156, v156
	v_add_u32_e32 v90, s15, v179
	ds_write_b128 v90, v[64:67] offset:49152
	ds_write_b128 v90, v[68:71] offset:61440
	s_waitcnt lgkmcnt(6)
	v_mfma_f32_32x32x16_bf16 v[16:31], v[196:199], v[218:221], v[16:31]
	v_fmamk_f32 v138, v138, 0x3dd53b94, v89
	v_fmamk_f32 v139, v139, 0x3dd53b94, v89
	v_exp_f32_e32 v157, v157
	v_fmamk_f32 v140, v140, 0x3dd53b94, v89
	v_fmamk_f32 v141, v141, 0x3dd53b94, v89
	v_add_u32_e32 v91, s15, v180
	s_waitcnt vmcnt(0)
	ds_write_b128 v91, v[72:75] offset:49152
	s_waitcnt lgkmcnt(5)
	v_mfma_f32_32x32x16_bf16 v[16:31], v[200:203], v[222:225], v[16:31]
	v_exp_f32_e32 v158, v158
	v_fmamk_f32 v142, v142, 0x3dd53b94, v89
	v_fmamk_f32 v143, v143, 0x3dd53b94, v89
	v_exp_f32_e32 v159, v159
	s_cbranch_vccz .Lattn_skip1
	s_and_saveexec_b64 s[12:13], s[4:5]
	ds_write_b32 v169, v249 offset:128
	s_or_b64 exec, exec, s[12:13]
	s_waitcnt lgkmcnt(0)
	v_add_u32_e32 v92, v168, v208
	ds_read_b128 v[64:67], v92 offset:128
	ds_read_b128 v[68:71], v92 offset:160
	ds_read_b128 v[72:75], v92 offset:192
	ds_read_b128 v[76:79], v92 offset:224
	s_waitcnt lgkmcnt(0)
	v_pk_mul_f32 v[0:1], v[0:1], v[64:65]
	v_pk_mul_f32 v[2:3], v[2:3], v[66:67]
	v_pk_mul_f32 v[4:5], v[4:5], v[68:69]
	v_pk_mul_f32 v[6:7], v[6:7], v[70:71]
	v_pk_mul_f32 v[8:9], v[8:9], v[72:73]
	v_pk_mul_f32 v[10:11], v[10:11], v[74:75]
	v_pk_mul_f32 v[12:13], v[12:13], v[76:77]
	v_pk_mul_f32 v[14:15], v[14:15], v[78:79]
	v_pk_mul_f32 v[48:49], v[48:49], v[64:65]
	v_pk_mul_f32 v[50:51], v[50:51], v[66:67]
	v_pk_mul_f32 v[52:53], v[52:53], v[68:69]
	v_pk_mul_f32 v[54:55], v[54:55], v[70:71]
	v_pk_mul_f32 v[56:57], v[56:57], v[72:73]
	v_pk_mul_f32 v[58:59], v[58:59], v[74:75]
	v_pk_mul_f32 v[60:61], v[60:61], v[76:77]
	v_pk_mul_f32 v[62:63], v[62:63], v[78:79]
	v_pk_mul_f32 v[32:33], v[32:33], v[64:65]
	v_pk_mul_f32 v[34:35], v[34:35], v[66:67]
	v_pk_mul_f32 v[36:37], v[36:37], v[68:69]
	v_pk_mul_f32 v[38:39], v[38:39], v[70:71]
	v_pk_mul_f32 v[40:41], v[40:41], v[72:73]
	v_pk_mul_f32 v[42:43], v[42:43], v[74:75]
	v_pk_mul_f32 v[44:45], v[44:45], v[76:77]
	v_pk_mul_f32 v[46:47], v[46:47], v[78:79]
	v_pk_mul_f32 v[16:17], v[16:17], v[64:65]
	v_pk_mul_f32 v[18:19], v[18:19], v[66:67]
	v_pk_mul_f32 v[20:21], v[20:21], v[68:69]
	v_pk_mul_f32 v[22:23], v[22:23], v[70:71]
	v_pk_mul_f32 v[24:25], v[24:25], v[72:73]
	v_pk_mul_f32 v[26:27], v[26:27], v[74:75]
	v_pk_mul_f32 v[28:29], v[28:29], v[76:77]
	v_pk_mul_f32 v[30:31], v[30:31], v[78:79]
.Lattn_skip1:
	s_waitcnt lgkmcnt(0)
	s_barrier
	s_mul_i32 s0, s9, 0x6000
	v_add_u32_e32 v250, s0, v173
	v_add_u32_e32 v251, s0, v181
	v_add_u32_e32 v252, s0, v182
	v_add_u32_e32 v172, s0, v183
	v_lshl_add_u32 v246, s49, 14, v171
	ds_read_b128 v[210:213], v250 offset:49152
	ds_read_b128 v[214:217], v250 offset:61440
	ds_read_b128 v[218:221], v251 offset:49152
	ds_read_b128 v[222:225], v251 offset:61440
	ds_read_b128 v[204:207], v252 offset:49152
	ds_read_b128 v[184:187], v252 offset:61440
	v_cvt_pk_bf16_f32 v188, v144, v145
	v_cvt_pk_bf16_f32 v189, v146, v147
	v_cvt_pk_bf16_f32 v190, v148, v149
	v_cvt_pk_bf16_f32 v191, v150, v151
	v_exp_f32_e32 v128, v128
	v_exp_f32_e32 v129, v129
	v_exp_f32_e32 v130, v130
	v_exp_f32_e32 v131, v131
	s_waitcnt lgkmcnt(5)
	v_mfma_f32_32x32x16_bf16 v[80:95], v[210:213], v[96:99], 0
	v_permlane32_swap_b32_e32 v188, v190
	v_permlane32_swap_b32_e32 v189, v191
	v_cvt_pk_bf16_f32 v192, v152, v153
	v_cvt_pk_bf16_f32 v193, v154, v155
	s_waitcnt lgkmcnt(4)
	v_mfma_f32_32x32x16_bf16 v[64:79], v[214:217], v[96:99], 0
	ds_read_b128 v[210:213], v172 offset:49152
	ds_read_b128 v[214:217], v172 offset:61440
	v_cvt_pk_bf16_f32 v194, v156, v157
	v_cvt_pk_bf16_f32 v195, v158, v159
	v_exp_f32_e32 v132, v132
	s_waitcnt lgkmcnt(5)
	v_mfma_f32_32x32x16_bf16 v[80:95], v[218:221], v[100:103], v[80:95]
	v_exp_f32_e32 v133, v133
	v_exp_f32_e32 v134, v134
	s_waitcnt lgkmcnt(4)
	v_mfma_f32_32x32x16_bf16 v[64:79], v[222:225], v[100:103], v[64:79]
	ds_read_b128 v[218:221], v250 offset:49280
	ds_read_b128 v[222:225], v250 offset:61568
	v_exp_f32_e32 v135, v135
	v_permlane32_swap_b32_e32 v192, v194
	s_waitcnt lgkmcnt(5)
	v_mfma_f32_32x32x16_bf16 v[80:95], v[204:207], v[104:107], v[80:95]
	v_permlane32_swap_b32_e32 v193, v195
	v_add_f32_e32 v255, v144, v145
	v_add_f32_e32 v255, v146, v255
	s_waitcnt lgkmcnt(4)
	v_mfma_f32_32x32x16_bf16 v[64:79], v[184:187], v[104:107], v[64:79]
	ds_read_b128 v[204:207], v251 offset:49280
	ds_read_b128 v[184:187], v251 offset:61568
	v_exp_f32_e32 v136, v136
	v_add_f32_e32 v255, v147, v255
	v_add_f32_e32 v255, v148, v255
	s_waitcnt lgkmcnt(5)
	v_mfma_f32_32x32x16_bf16 v[80:95], v[210:213], v[116:119], v[80:95]
	v_exp_f32_e32 v137, v137
	v_add_f32_e32 v255, v149, v255
	v_add_f32_e32 v255, v150, v255
	s_waitcnt lgkmcnt(4)
; #define SBAR() __builtin_amdgcn_sched_barrier(0)
; #define SLOAD(k0) do { const long rb = KROW(k0); const bf16* pn = KN + (rb + sr) * LDKN + sc; \
;     ks0 = *reinterpret_cast<const bf16x8*>(pn); ks1 = *reinterpret_cast<const bf16x8*>(pn + 32 * LDKN); vs0 = *reinterpret_cast<const bf16x8*>(pn + 128); vs1 = *reinterpret_cast<const bf16x8*>(pn + 32 * LDKN + 128); \
;     ks2 = *reinterpret_cast<const bf16x8*>(KR + rb * LDKR + tid * 8); } while (0)
; __device__ __forceinline__ void qkt(f32x16& p0, f32x16& p1, const char* Ks, const bf16x8* qr, const bf16x8* qs, const int* kb) {
;   p0 = f32x16{}; p1 = f32x16{};
; #pragma unroll
;   for (int d0 = 0; d0 < 12; ++d0) { const int off = kb[d0 & 3] + (d0 >> 2) * 128;
;     bf16x8 b0 = *reinterpret_cast<const bf16x8*>(Ks + off);
;     bf16x8 b1 = *reinterpret_cast<const bf16x8*>(Ks + off + 32 * 384);
;     const bf16x8 q = d0 < 8 ? qr[d0 < 8 ? d0 : 0] : qs[(d0 - 8) * 64];
;     p0 = __builtin_amdgcn_mfma_f32_32x32x16_bf16(b0, q, p0, 0, 0, 0);
;     p1 = __builtin_amdgcn_mfma_f32_32x32x16_bf16(b1, q, p1, 0, 0, 0); }
; __device__ __forceinline__ void attn_unit(const bf16* __restrict__ Qb, const bf16* __restrict__ KN, const bf16* __restrict__ KR, ...
;     ...
;     SBAR(); qkt(pA0, pA1, K_lds + rc * SHM_K, qr, qs, kb);
;     finishSM(pB0, pB1, alB, l_reg, pa0, pa1, pa2, pa3); SBAR();
;     SLOAD((j + 2) * KVBLK); SBAR();
;     pv_d0(o, vb0 + rp * SHM_V, pa0, pa1, pa2, pa3); partialSM(pA0, pA1, m_reg, mnA, alA);
	v_mfma_f32_32x32x16_bf16 v[64:79], v[214:217], v[116:119], v[64:79]
	ds_read_b128 v[210:213], v252 offset:49280
	ds_read_b128 v[214:217], v252 offset:61568
	v_exp_f32_e32 v138, v138
	v_add_f32_e32 v255, v151, v255
	s_waitcnt lgkmcnt(5)
	v_mfma_f32_32x32x16_bf16 v[80:95], v[218:221], v[108:111], v[80:95]
	v_add_f32_e32 v255, v152, v255
	v_exp_f32_e32 v139, v139
	v_add_f32_e32 v255, v153, v255
	s_waitcnt lgkmcnt(4)
	v_mfma_f32_32x32x16_bf16 v[64:79], v[222:225], v[108:111], v[64:79]
	ds_read_b128 v[218:221], v172 offset:49280
	ds_read_b128 v[222:225], v172 offset:61568
	v_add_f32_e32 v255, v154, v255
	v_exp_f32_e32 v140, v140
	s_waitcnt lgkmcnt(5)
	v_mfma_f32_32x32x16_bf16 v[80:95], v[204:207], v[112:115], v[80:95]
	v_add_f32_e32 v255, v155, v255
	v_add_f32_e32 v255, v156, v255
	v_exp_f32_e32 v141, v141
	s_waitcnt lgkmcnt(4)
	v_mfma_f32_32x32x16_bf16 v[64:79], v[184:187], v[112:115], v[64:79]
	ds_read_b128 v[204:207], v250 offset:49408
	ds_read_b128 v[184:187], v250 offset:61696
	v_add_f32_e32 v255, v157, v255
	v_add_f32_e32 v255, v158, v255
	v_exp_f32_e32 v142, v142
	s_waitcnt lgkmcnt(5)
	v_mfma_f32_32x32x16_bf16 v[80:95], v[210:213], v[120:123], v[80:95]
	v_add_f32_e32 v255, v159, v255
	v_exp_f32_e32 v143, v143
	s_waitcnt lgkmcnt(4)
	v_mfma_f32_32x32x16_bf16 v[64:79], v[214:217], v[120:123], v[64:79]
	ds_read_b128 v[210:213], v251 offset:49408
	ds_read_b128 v[214:217], v251 offset:61696
	v_cvt_pk_bf16_f32 v196, v128, v129
	v_cvt_pk_bf16_f32 v197, v130, v131
	v_cvt_pk_bf16_f32 v198, v132, v133
	v_cvt_pk_bf16_f32 v199, v134, v135
	s_waitcnt lgkmcnt(5)
	v_mfma_f32_32x32x16_bf16 v[80:95], v[218:221], v[124:127], v[80:95]
	v_add_f32_e32 v203, v128, v129
	v_add_f32_e32 v203, v130, v203
	v_add_f32_e32 v203, v131, v203
	s_waitcnt lgkmcnt(4)
	v_mfma_f32_32x32x16_bf16 v[64:79], v[222:225], v[124:127], v[64:79]
	ds_read_b128 v[218:221], v252 offset:49408
	ds_read_b128 v[222:225], v252 offset:61696
	v_add_f32_e32 v203, v132, v203
	v_add_f32_e32 v203, v133, v203
	v_add_f32_e32 v203, v134, v203
	v_add_f32_e32 v203, v135, v203
	s_waitcnt lgkmcnt(5)
	v_mfma_f32_32x32x16_bf16 v[80:95], v[204:207], v[226:229], v[80:95]
	v_add_f32_e32 v203, v136, v203
	v_permlane32_swap_b32_e32 v196, v198
	v_permlane32_swap_b32_e32 v197, v199
	v_add_f32_e32 v203, v137, v203
	s_waitcnt lgkmcnt(4)
	v_mfma_f32_32x32x16_bf16 v[64:79], v[184:187], v[226:229], v[64:79]
	ds_read_b128 v[204:207], v172 offset:49408
	ds_read_b128 v[184:187], v172 offset:61696
	v_add_f32_e32 v203, v138, v203
	v_add_f32_e32 v203, v139, v203
	v_add_f32_e32 v203, v140, v203
	s_waitcnt lgkmcnt(5)
	v_mfma_f32_32x32x16_bf16 v[80:95], v[210:213], v[230:233], v[80:95]
	v_add_f32_e32 v203, v141, v203
	v_add_f32_e32 v203, v142, v203
	v_add_f32_e32 v203, v143, v203
	v_add_f32_e32 v255, v255, v203
	s_waitcnt lgkmcnt(4)
	v_mfma_f32_32x32x16_bf16 v[64:79], v[214:217], v[230:233], v[64:79]
	ds_read_b64_tr_b16 v[210:211], v246 offset:0
	ds_read_b64_tr_b16 v[212:213], v246 offset:2048
	ds_read_b64_tr_b16 v[214:215], v246 offset:4096
	ds_read_b64_tr_b16 v[216:217], v246 offset:6144
	v_mov_b32_e32 v202, v255
	s_nop 1
	v_permlane32_swap_b32_e32 v255, v202
	v_add_f32_e32 v255, v255, v202
	s_waitcnt lgkmcnt(7)
	v_mfma_f32_32x32x16_bf16 v[80:95], v[218:221], v[234:237], v[80:95]
	v_fma_f32 v170, v170, v249, v255
	v_cvt_pk_bf16_f32 v200, v136, v137
	v_cvt_pk_bf16_f32 v201, v138, v139
	v_cvt_pk_bf16_f32 v202, v140, v141
	s_waitcnt lgkmcnt(6)
	v_mfma_f32_32x32x16_bf16 v[64:79], v[222:225], v[234:237], v[64:79]
	ds_read_b64_tr_b16 v[218:219], v246 offset:8192
	ds_read_b64_tr_b16 v[220:221], v246 offset:10240
	ds_read_b64_tr_b16 v[222:223], v246 offset:12288
	ds_read_b64_tr_b16 v[224:225], v246 offset:14336
	v_cvt_pk_bf16_f32 v203, v142, v143
	v_permlane32_swap_b32_e32 v200, v202
	s_nop 0
	v_permlane32_swap_b32_e32 v201, v203
	s_waitcnt lgkmcnt(9)
	v_mfma_f32_32x32x16_bf16 v[80:95], v[204:207], v[238:241], v[80:95]
	s_waitcnt lgkmcnt(8)
	v_mfma_f32_32x32x16_bf16 v[64:79], v[184:187], v[238:241], v[64:79]
	ds_read_b64_tr_b16 v[204:205], v246 offset:512
	ds_read_b64_tr_b16 v[206:207], v246 offset:2560
	ds_read_b64_tr_b16 v[184:185], v246 offset:4608
	ds_read_b64_tr_b16 v[186:187], v246 offset:6656
	s_add_i32 s0, s10, 64
	s_cmp_lt_u32 s0, s42
	s_cselect_b32 s1, s44, s45
	s_add_i32 s0, s0, s1
	s_ashr_i32 s1, s0, 31
	v_lshl_add_u64 v[128:129], s[0:1], 0, v[162:163]
	v_lshlrev_b64 v[128:129], 11, v[128:129]
	v_lshl_add_u64 v[132:133], v[164:165], 0, v[128:129]
	v_add_co_u32_e32 v136, vcc, s73, v132
	s_lshl_b64 s[0:1], s[0:1], 7
	s_nop 0
	v_addc_co_u32_e32 v137, vcc, 0, v133, vcc
	global_load_dwordx4 v[128:131], v[132:133], off
	global_load_dwordx4 v[140:143], v[132:133], off offset:256
	s_nop 0
	global_load_dwordx4 v[132:135], v[136:137], off
	global_load_dwordx4 v[144:147], v[136:137], off offset:256
	v_lshl_add_u64 v[136:137], v[166:167], 0, s[0:1]
	global_load_dwordx4 v[136:139], v[136:137], off
	s_lshl_b32 s14, s8, 14
	s_lshl_b32 s1, s8, 13
	s_add_i32 s15, s14, s1
	s_waitcnt lgkmcnt(10)
	v_mfma_f32_32x32x16_bf16 v[0:15], v[188:191], v[210:213], v[0:15]
	ds_read_b64_tr_b16 v[210:211], v246 offset:8704
	ds_read_b64_tr_b16 v[212:213], v246 offset:10752
	v_max3_f32 v148, v80, v81, v82
	v_max3_f32 v149, v64, v65, v66
	v_max3_f32 v148, v148, v83, v84
	v_max3_f32 v149, v149, v67, v68
	v_max3_f32 v148, v148, v85, v86
	v_max3_f32 v149, v149, v69, v70
	s_waitcnt lgkmcnt(10)
	v_mfma_f32_32x32x16_bf16 v[0:15], v[192:195], v[214:217], v[0:15]
	ds_read_b64_tr_b16 v[214:215], v246 offset:12800
	ds_read_b64_tr_b16 v[216:217], v246 offset:14848
	v_max3_f32 v148, v148, v87, v88
	v_max3_f32 v149, v149, v71, v72
	v_max3_f32 v148, v148, v89, v90
	v_max3_f32 v149, v149, v73, v74
	v_max3_f32 v148, v148, v91, v92
	v_max3_f32 v149, v149, v75, v76
	s_waitcnt lgkmcnt(10)
; #define SWRITE(b) do { *(bf16x8*)(V_lds + (b) * SHM_V + vst0) = vs0; *(bf16x8*)(V_lds + (b) * SHM_V + vst1) = vs1; \
;     *(bf16x8*)(K_lds + (b) * SHM_K + knd0) = ks0; *(bf16x8*)(K_lds + (b) * SHM_K + knd1) = ks1; *(bf16x8*)(K_lds + (b) * SHM_K + krd) = ks2; } while (0)
; #define RESC(a) do { if (__any((a) < 1.f)) { if (hi == 0) al_l[r32] = (a); asm volatile("s_waitcnt lgkmcnt(0)" ::: "memory"); \
;     for (int d = 0; d < 4; ++d) for (int r = 0; r < 16; ++r) o[d][r] *= al_l[crow(r, hi)]; } } while (0)
; __device__ __forceinline__ void partialSM(f32x16& p0, f32x16& p1, float& m_reg, float& mn, float& alpha) {
;   constexpr float C = SCALE * 1.4426950408889634f;
;   float pmax = p0[0]; for (int r = 1; r < 16; ++r) pmax = fmaxf(pmax, p0[r]); for (int r = 0; r < 16; ++r) pmax = fmaxf(pmax, p1[r]);
;   { auto rr = __builtin_amdgcn_permlane32_swap(__float_as_uint(pmax), __float_as_uint(pmax), false, false);
;     pmax = fmaxf(__uint_as_float(rr[0]), __uint_as_float(rr[1])); }
;   if (__builtin_expect(__all(pmax - m_reg <= THR / SCALE), 1)) { mn = m_reg; alpha = 1.f; }
;   else { mn = fmaxf(m_reg, pmax); alpha = __builtin_amdgcn_exp2f((m_reg - mn) * C); m_reg = mn; }
;   float mnC = -mn * C;
;   for (int r = 0; r < 16; ++r) p0[r] = fmaf(p0[r], C, mnC); for (int r = 0; r < 16; ++r) p1[r] = fmaf(p1[r], C, mnC);
;   for (int r = 0; r < 16; ++r) p0[r] = __builtin_amdgcn_exp2f(p0[r]);
; }
; __device__ __forceinline__ void attn_unit(const bf16* __restrict__ Qb, const bf16* __restrict__ KN, const bf16* __restrict__ KR, ...
;     ...
;     pv_d0(o, vb0 + rp * SHM_V, pa0, pa1, pa2, pa3); partialSM(pA0, pA1, m_reg, mnA, alA);
;     SWRITE(rn);
;     RESC(alA); __syncthreads();
	v_mfma_f32_32x32x16_bf16 v[0:15], v[196:199], v[218:221], v[0:15]
	ds_read_b64_tr_b16 v[218:219], v246 offset:1024
	ds_read_b64_tr_b16 v[220:221], v246 offset:3072
	v_max3_f32 v148, v148, v93, v94
	v_max3_f32 v149, v149, v77, v78
	v_max_f32_e32 v148, v148, v95
	v_max_f32_e32 v149, v149, v79
	v_max_f32_e32 v148, v148, v149
	v_mov_b32_e32 v150, v148
	s_waitcnt lgkmcnt(10)
	v_mfma_f32_32x32x16_bf16 v[0:15], v[200:203], v[222:225], v[0:15]
	ds_read_b64_tr_b16 v[222:223], v246 offset:5120
	ds_read_b64_tr_b16 v[224:225], v246 offset:7168
	v_permlane32_swap_b32_e32 v148, v150
	v_max_f32_e32 v148, v148, v150
	v_sub_f32_e32 v151, v148, v178
	v_cmp_ge_f32_e32 vcc, s74, v151
	v_max_f32_e32 v152, v178, v148
	v_sub_f32_e32 v151, v178, v152
	s_waitcnt lgkmcnt(10)
	v_mfma_f32_32x32x16_bf16 v[48:63], v[188:191], v[204:207], v[48:63]
	ds_read_b64_tr_b16 v[204:205], v246 offset:9216
	ds_read_b64_tr_b16 v[206:207], v246 offset:11264
	v_mul_f32_e32 v151, 0x3dd53b94, v151
	v_exp_f32_e32 v151, v151
	s_cmp_eq_u64 vcc, exec
	s_cselect_b64 s[6:7], -1, 0
	v_cndmask_b32_e64 v249, v151, 1.0, s[6:7]
	v_cndmask_b32_e64 v178, v152, v178, s[6:7]
	s_waitcnt lgkmcnt(10)
	v_mfma_f32_32x32x16_bf16 v[48:63], v[192:195], v[184:187], v[48:63]
	ds_read_b64_tr_b16 v[184:185], v246 offset:13312
	ds_read_b64_tr_b16 v[186:187], v246 offset:15360
	v_mul_f32_e32 v153, 0xbdd53b94, v178
	v_cmp_gt_f32_e32 vcc, 1.0, v249
	v_fmamk_f32 v80, v80, 0x3dd53b94, v153
	v_fmamk_f32 v81, v81, 0x3dd53b94, v153
	v_fmamk_f32 v82, v82, 0x3dd53b94, v153
	v_fmamk_f32 v83, v83, 0x3dd53b94, v153
	s_waitcnt lgkmcnt(10)
	v_mfma_f32_32x32x16_bf16 v[48:63], v[196:199], v[210:213], v[48:63]
	ds_read_b64_tr_b16 v[210:211], v246 offset:1536
	ds_read_b64_tr_b16 v[212:213], v246 offset:3584
	v_fmamk_f32 v84, v84, 0x3dd53b94, v153
	v_fmamk_f32 v85, v85, 0x3dd53b94, v153
	v_fmamk_f32 v86, v86, 0x3dd53b94, v153
	v_fmamk_f32 v87, v87, 0x3dd53b94, v153
	v_fmamk_f32 v88, v88, 0x3dd53b94, v153
	v_exp_f32_e32 v80, v80
	s_waitcnt lgkmcnt(10)
	v_mfma_f32_32x32x16_bf16 v[48:63], v[200:203], v[214:217], v[48:63]
	ds_read_b64_tr_b16 v[214:215], v246 offset:5632
	ds_read_b64_tr_b16 v[216:217], v246 offset:7680
	v_fmamk_f32 v89, v89, 0x3dd53b94, v153
	v_exp_f32_e32 v81, v81
	v_fmamk_f32 v90, v90, 0x3dd53b94, v153
	v_exp_f32_e32 v82, v82
	s_waitcnt lgkmcnt(10)
	v_mfma_f32_32x32x16_bf16 v[32:47], v[188:191], v[218:221], v[32:47]
	ds_read_b64_tr_b16 v[218:219], v246 offset:9728
	ds_read_b64_tr_b16 v[220:221], v246 offset:11776
	v_fmamk_f32 v91, v91, 0x3dd53b94, v153
	v_exp_f32_e32 v83, v83
	v_fmamk_f32 v92, v92, 0x3dd53b94, v153
	v_exp_f32_e32 v84, v84
	s_waitcnt lgkmcnt(10)
	v_mfma_f32_32x32x16_bf16 v[32:47], v[192:195], v[222:225], v[32:47]
	ds_read_b64_tr_b16 v[222:223], v246 offset:13824
	ds_read_b64_tr_b16 v[224:225], v246 offset:15872
	v_fmamk_f32 v93, v93, 0x3dd53b94, v153
	v_exp_f32_e32 v85, v85
	v_fmamk_f32 v94, v94, 0x3dd53b94, v153
	v_exp_f32_e32 v86, v86
	s_waitcnt lgkmcnt(10)
	v_mfma_f32_32x32x16_bf16 v[32:47], v[196:199], v[204:207], v[32:47]
	v_fmamk_f32 v95, v95, 0x3dd53b94, v153
	v_exp_f32_e32 v87, v87
	v_fmamk_f32 v64, v64, 0x3dd53b94, v153
	v_fmamk_f32 v65, v65, 0x3dd53b94, v153
	s_waitcnt lgkmcnt(8)
	v_mfma_f32_32x32x16_bf16 v[32:47], v[200:203], v[184:187], v[32:47]
	v_exp_f32_e32 v88, v88
	v_fmamk_f32 v66, v66, 0x3dd53b94, v153
	v_fmamk_f32 v67, v67, 0x3dd53b94, v153
	v_exp_f32_e32 v89, v89
	v_add_u32_e32 v154, s14, v174
	s_waitcnt vmcnt(3)
	ds_write_b128 v154, v[140:143]
	s_waitcnt lgkmcnt(7)
	v_mfma_f32_32x32x16_bf16 v[16:31], v[188:191], v[210:213], v[16:31]
	v_fmamk_f32 v68, v68, 0x3dd53b94, v153
	v_fmamk_f32 v69, v69, 0x3dd53b94, v153
	v_exp_f32_e32 v90, v90
	v_fmamk_f32 v70, v70, 0x3dd53b94, v153
	v_fmamk_f32 v71, v71, 0x3dd53b94, v153
	v_add_u32_e32 v155, s14, v175
	s_waitcnt vmcnt(1)
	ds_write_b128 v155, v[144:147]
	s_waitcnt lgkmcnt(6)
	v_mfma_f32_32x32x16_bf16 v[16:31], v[192:195], v[214:217], v[16:31]
	v_exp_f32_e32 v91, v91
	v_fmamk_f32 v72, v72, 0x3dd53b94, v153
	v_fmamk_f32 v73, v73, 0x3dd53b94, v153
	v_exp_f32_e32 v92, v92
	v_add_u32_e32 v154, s15, v179
	ds_write_b128 v154, v[128:131] offset:49152
	ds_write_b128 v154, v[132:135] offset:61440
	s_waitcnt lgkmcnt(6)
	v_mfma_f32_32x32x16_bf16 v[16:31], v[196:199], v[218:221], v[16:31]
	v_fmamk_f32 v74, v74, 0x3dd53b94, v153
	v_fmamk_f32 v75, v75, 0x3dd53b94, v153
	v_exp_f32_e32 v93, v93
	v_fmamk_f32 v76, v76, 0x3dd53b94, v153
	v_fmamk_f32 v77, v77, 0x3dd53b94, v153
	v_add_u32_e32 v155, s15, v180
	s_waitcnt vmcnt(0)
	ds_write_b128 v155, v[136:139] offset:49152
	s_waitcnt lgkmcnt(5)
	v_mfma_f32_32x32x16_bf16 v[16:31], v[200:203], v[222:225], v[16:31]
	v_exp_f32_e32 v94, v94
	v_fmamk_f32 v78, v78, 0x3dd53b94, v153
	v_fmamk_f32 v79, v79, 0x3dd53b94, v153
	v_exp_f32_e32 v95, v95
	s_cbranch_vccz .Lattn_skip2
	s_and_saveexec_b64 s[12:13], s[4:5]
	ds_write_b32 v169, v249 offset:128
	s_or_b64 exec, exec, s[12:13]
	s_waitcnt lgkmcnt(0)
	v_add_u32_e32 v156, v168, v208
	ds_read_b128 v[128:131], v156 offset:128
	ds_read_b128 v[132:135], v156 offset:160
	ds_read_b128 v[136:139], v156 offset:192
	ds_read_b128 v[140:143], v156 offset:224
	s_waitcnt lgkmcnt(0)
	v_pk_mul_f32 v[0:1], v[0:1], v[128:129]
	v_pk_mul_f32 v[2:3], v[2:3], v[130:131]
	v_pk_mul_f32 v[4:5], v[4:5], v[132:133]
	v_pk_mul_f32 v[6:7], v[6:7], v[134:135]
	v_pk_mul_f32 v[8:9], v[8:9], v[136:137]
	v_pk_mul_f32 v[10:11], v[10:11], v[138:139]
	v_pk_mul_f32 v[12:13], v[12:13], v[140:141]
	v_pk_mul_f32 v[14:15], v[14:15], v[142:143]
	v_pk_mul_f32 v[48:49], v[48:49], v[128:129]
	v_pk_mul_f32 v[50:51], v[50:51], v[130:131]
	v_pk_mul_f32 v[52:53], v[52:53], v[132:133]
	v_pk_mul_f32 v[54:55], v[54:55], v[134:135]
	v_pk_mul_f32 v[56:57], v[56:57], v[136:137]
	v_pk_mul_f32 v[58:59], v[58:59], v[138:139]
	v_pk_mul_f32 v[60:61], v[60:61], v[140:141]
	v_pk_mul_f32 v[62:63], v[62:63], v[142:143]
	v_pk_mul_f32 v[32:33], v[32:33], v[128:129]
	v_pk_mul_f32 v[34:35], v[34:35], v[130:131]
	v_pk_mul_f32 v[36:37], v[36:37], v[132:133]
	v_pk_mul_f32 v[38:39], v[38:39], v[134:135]
	v_pk_mul_f32 v[40:41], v[40:41], v[136:137]
	v_pk_mul_f32 v[42:43], v[42:43], v[138:139]
	v_pk_mul_f32 v[44:45], v[44:45], v[140:141]
	v_pk_mul_f32 v[46:47], v[46:47], v[142:143]
	v_pk_mul_f32 v[16:17], v[16:17], v[128:129]
	v_pk_mul_f32 v[18:19], v[18:19], v[130:131]
	v_pk_mul_f32 v[20:21], v[20:21], v[132:133]
	v_pk_mul_f32 v[22:23], v[22:23], v[134:135]
	v_pk_mul_f32 v[24:25], v[24:25], v[136:137]
	v_pk_mul_f32 v[26:27], v[26:27], v[138:139]
	v_pk_mul_f32 v[28:29], v[28:29], v[140:141]
	v_pk_mul_f32 v[30:31], v[30:31], v[142:143]
; #define SBAR() __builtin_amdgcn_sched_barrier(0)
; #define RESC(a) do { if (__any((a) < 1.f)) { if (hi == 0) al_l[r32] = (a); asm volatile("s_waitcnt lgkmcnt(0)" ::: "memory"); \
;     for (int d = 0; d < 4; ++d) for (int r = 0; r < 16; ++r) o[d][r] *= al_l[crow(r, hi)]; } } while (0)
; __device__ __forceinline__ void attn_unit(const bf16* __restrict__ Qb, const bf16* __restrict__ KN, const bf16* __restrict__ KR, ...
;     ...
;     RESC(alA); __syncthreads();
;     { const int t = rp; rp = rc; rc = rn; rn = t; }
;   }
;   SBAR(); qkt(pB0, pB1, K_lds + rc * SHM_K, qr, qs, kb);
;   finishSM(pA0, pA1, alA, l_reg, pa0, pa1, pa2, pa3); SBAR();
;   pv_d0(o, vb0 + rp * SHM_V, pa0, pa1, pa2, pa3); partialSM(pB0, pB1, m_reg, mnB, alB);
.Lattn_skip2:
	s_add_u32 s10, s10, 0x80
	s_addc_u32 s11, s11, 0
	s_add_i32 s48, s48, 2
	s_cmp_ge_u32 s48, s43
	s_waitcnt lgkmcnt(0)
	s_barrier
	s_cbranch_scc1 .Lattn_exit
	s_mov_b32 s0, s49
	s_mov_b32 s49, s8
	s_mov_b32 s8, s9
	s_mov_b32 s9, s0
	s_branch .LBB0_107
.Lattn_exit:
	v_mov_b32_e32 v149, v80
	v_mov_b32_e32 v150, v81
	v_mov_b32_e32 v151, v82
	v_mov_b32_e32 v157, v83
	v_mov_b32_e32 v159, v84
	v_mov_b32_e32 v188, v85
	v_mov_b32_e32 v152, v86
	v_mov_b32_e32 v158, v87
	v_mov_b32_e32 v144, v88
	v_mov_b32_e32 v146, v89
	v_mov_b32_e32 v153, v90
	v_mov_b32_e32 v154, v91
	v_mov_b32_e32 v145, v92
	v_mov_b32_e32 v147, v93
	v_mov_b32_e32 v155, v94
	v_mov_b32_e32 v156, v95
	v_mov_b32_e32 v142, v64
	v_mov_b32_e32 v143, v65
	v_mov_b32_e32 v140, v66
	v_mov_b32_e32 v141, v67
	v_mov_b32_e32 v138, v68
	v_mov_b32_e32 v139, v69
	v_mov_b32_e32 v136, v70
	v_mov_b32_e32 v137, v71
	v_mov_b32_e32 v134, v72
	v_mov_b32_e32 v135, v73
	v_mov_b32_e32 v132, v74
	v_mov_b32_e32 v133, v75
	v_mov_b32_e32 v130, v76
	v_mov_b32_e32 v131, v77
	v_mov_b32_e32 v128, v78
	v_mov_b32_e32 v129, v79
	v_mov_b32_e32 v148, v249
	s_lshl_b32 s14, s9, 14
	s_mul_i32 s0, s8, 0x6000
	v_lshl_add_u32 v172, s8, 14, v171
